# GEMM K-loops: duplicate post-barrier lgkmcnt(0) removed on top of setprio-flip removal
# speedup vs baseline: 1.0049x; 1.0049x over previous
; #define PG8_STAGE(bufoff, gbase, voff) do { _Pragma("unroll") for (int _i = 0; _i < 2; ++_i) \
;         __builtin_amdgcn_global_load_lds((const unsigned*)((const char*)(gbase) + (voff)[_i]), (PG8_LAS unsigned*)(lds + (bufoff) + ldsw + _i * 8192), 16, 0, 0); } while (0)
; #define PG8_LDA(dst, b, h) do { _Pragma("unroll") for (int m = 0; m < 4; ++m) _Pragma("unroll") for (int k = 0; k < 2; ++k) dst[m][k] = *(const PG8_LAS bf16x8*)(lds + PG8_SA(b, h) + aoff + m * 2048 + k * 1024); } while (0)
; #define PG8_LDB(dst, b, h) do { _Pragma("unroll") for (int n = 0; n < 2; ++n) _Pragma("unroll") for (int k = 0; k < 2; ++k) dst[n][k] = *(const PG8_LAS bf16x8*)(lds + PG8_SB(b, h) + boff + n * 2048 + k * 1024); } while (0)
; #define PG8_MMA(ai, bj, At, Bt) do { __builtin_amdgcn_s_setprio(1); _Pragma("unroll") for (int m = 0; m < 4; ++m) _Pragma("unroll") for (int n = 0; n < 2; ++n) _Pragma("unroll") for (int k = 0; k < 2; ++k) \
;         acc[ai][bj][m][n] = __builtin_amdgcn_mfma_f32_16x16x32_bf16(Bt[n][k], At[m][k], acc[ai][bj][m][n], 0, 0, 0); __builtin_amdgcn_s_setprio(0); } while (0)
; #define PG8_WAIT_V(n) asm volatile("s_waitcnt vmcnt(" #n ")" ::: "memory")
; #define PG8_WAIT_L(n) asm volatile("s_waitcnt lgkmcnt(" #n ")" ::: "memory")
; template <class Epi, class Sched, bool ALIGN_EPI = false, bool SP2 = false>
; __device__ __forceinline__ void gemm_phase(PG8_LAS unsigned char* lds, const Gemm g, const Sched& S, const Epi& E) {
;     ...
;             const bool last = (t == nt - 2);
;             const char* a1 = cA + (size_t)(t + 1) * kstep;
;             const char* a2 = last ? nA : cA + (size_t)(t + 2) * kstep; const char* b2 = last ? nB : cB + (size_t)(t + 2) * kstep;
;             const char* a3 = a2 + kstep; const char* b3 = b2 + kstep;
;             if (last && has_next) S.a_ready(nxt);
;             if constexpr (SP2) {
;             PG8_LDB(B0, 0, 0); PG8_LDB(B1, 0, 1); PG8_SCHED; PG8_LDA(At, 0, 0); PG8_STAGE(PG8_SA(1, 1), a1 + hstep, voffA);
;             PG8_WAIT_V(8); PG8_WAIT_L(0); PG8_BAR; PG8_MMA(0, 0, At, B0); PG8_MMA(0, 1, At, B1); PG8_BAR; PG8_SCHED;
;             PG8_LDA(At, 0, 1); PG8_STAGE(PG8_SB(0, 0), b2, voffB); PG8_STAGE(PG8_SB(0, 1), b2 + hstep, voffB); PG8_STAGE(PG8_SA(0, 0), a2, voffA);
;             PG8_WAIT_V(8); PG8_WAIT_L(0); PG8_BAR; PG8_MMA(1, 0, At, B0); PG8_MMA(1, 1, At, B1); PG8_BAR; PG8_SCHED;
.LBB0_143:
	s_add_u32 s56, s4, 0xfffc0080
	s_addc_u32 s57, s5, -1
	s_add_i32 s63, 0, 0x10000
	s_cmp_eq_u32 s62, 12
	s_cselect_b32 s59, s31, s57
	s_cselect_b32 s58, s33, s56
	s_cselect_b32 s57, s34, s51
	s_cselect_b32 s56, s35, s49
	s_add_i32 s66, 0, 0x14000
	v_add_u32_e32 v140, s63, v249
	v_add_u32_e32 v156, s66, v249
	ds_read_b128 v[128:131], v140
	ds_read_b128 v[132:135], v140 offset:1024
	ds_read_b128 v[136:139], v140 offset:2048
	ds_read_b128 v[140:143], v140 offset:3072
	ds_read_b128 v[144:147], v156
	ds_read_b128 v[148:151], v156 offset:1024
	ds_read_b128 v[152:155], v156 offset:2048
	ds_read_b128 v[156:159], v156 offset:3072
	v_lshl_add_u64 v[178:179], s[4:5], 0, v[206:207]
	s_add_i32 m0, s11, 0xc000
	ds_read_b128 v[160:163], v245
	ds_read_b128 v[164:167], v245 offset:1024
	ds_read_b128 v[168:171], v245 offset:2048
	ds_read_b128 v[172:175], v245 offset:3072
	ds_read_b128 v[208:211], v245 offset:4096
	ds_read_b128 v[212:215], v245 offset:5120
	ds_read_b128 v[216:219], v245 offset:6144
	ds_read_b128 v[220:223], v245 offset:7168
	global_load_lds_dwordx4 v[178:179], off
	v_lshl_add_u64 v[178:179], s[4:5], 0, v[204:205]
	s_add_i32 m0, s11, 0xe000
	s_nop 0
	global_load_lds_dwordx4 v[178:179], off
	s_waitcnt vmcnt(8)
	s_waitcnt lgkmcnt(0)
	s_barrier
	v_mfma_f32_16x16x32_bf16 v[124:127], v[128:131], v[160:163], v[124:127]
	v_mfma_f32_16x16x32_bf16 v[120:123], v[136:139], v[160:163], v[120:123]
	v_mfma_f32_16x16x32_bf16 v[108:111], v[128:131], v[168:171], v[108:111]
	v_mfma_f32_16x16x32_bf16 v[104:107], v[136:139], v[168:171], v[104:107]
	v_mfma_f32_16x16x32_bf16 v[92:95], v[128:131], v[208:211], v[92:95]
	v_mfma_f32_16x16x32_bf16 v[88:91], v[136:139], v[208:211], v[88:91]
	v_mfma_f32_16x16x32_bf16 v[76:79], v[128:131], v[216:219], v[76:79]
	v_mfma_f32_16x16x32_bf16 v[72:75], v[136:139], v[216:219], v[72:75]
	v_mfma_f32_16x16x32_bf16 v[124:127], v[132:135], v[164:167], v[124:127]
	v_mfma_f32_16x16x32_bf16 v[120:123], v[140:143], v[164:167], v[120:123]
	v_mfma_f32_16x16x32_bf16 v[108:111], v[132:135], v[172:175], v[108:111]
	v_mfma_f32_16x16x32_bf16 v[104:107], v[140:143], v[172:175], v[104:107]
	v_mfma_f32_16x16x32_bf16 v[92:95], v[132:135], v[212:215], v[92:95]
	v_mfma_f32_16x16x32_bf16 v[88:91], v[140:143], v[212:215], v[88:91]
	v_mfma_f32_16x16x32_bf16 v[76:79], v[132:135], v[220:223], v[76:79]
	v_mfma_f32_16x16x32_bf16 v[72:75], v[140:143], v[220:223], v[72:75]
	v_mfma_f32_16x16x32_bf16 v[116:119], v[144:147], v[160:163], v[116:119]
	v_mfma_f32_16x16x32_bf16 v[112:115], v[152:155], v[160:163], v[112:115]
	v_mfma_f32_16x16x32_bf16 v[100:103], v[144:147], v[168:171], v[100:103]
	v_mfma_f32_16x16x32_bf16 v[96:99], v[152:155], v[168:171], v[96:99]
	v_mfma_f32_16x16x32_bf16 v[84:87], v[144:147], v[208:211], v[84:87]
	v_mfma_f32_16x16x32_bf16 v[80:83], v[152:155], v[208:211], v[80:83]
	v_mfma_f32_16x16x32_bf16 v[68:71], v[144:147], v[216:219], v[68:71]
	v_mfma_f32_16x16x32_bf16 v[64:67], v[152:155], v[216:219], v[64:67]
	v_mfma_f32_16x16x32_bf16 v[116:119], v[148:151], v[164:167], v[116:119]
	v_mfma_f32_16x16x32_bf16 v[112:115], v[156:159], v[164:167], v[112:115]
	v_mfma_f32_16x16x32_bf16 v[100:103], v[148:151], v[172:175], v[100:103]
	v_mfma_f32_16x16x32_bf16 v[96:99], v[156:159], v[172:175], v[96:99]
	v_mfma_f32_16x16x32_bf16 v[84:87], v[148:151], v[212:215], v[84:87]
	v_mfma_f32_16x16x32_bf16 v[80:83], v[156:159], v[212:215], v[80:83]
	v_mfma_f32_16x16x32_bf16 v[68:71], v[148:151], v[220:223], v[68:71]
	v_mfma_f32_16x16x32_bf16 v[64:67], v[156:159], v[220:223], v[64:67]
	s_barrier
	s_add_i32 s63, s63, s2
	v_lshl_add_u64 v[178:179], s[56:57], 0, v[198:199]
	s_mov_b32 m0, s63
	ds_read_b128 v[160:163], v245 offset:16384
	ds_read_b128 v[164:167], v245 offset:17408
	ds_read_b128 v[168:171], v245 offset:18432
	ds_read_b128 v[172:175], v245 offset:19456
	ds_read_b128 v[208:211], v245 offset:20480
	ds_read_b128 v[212:215], v245 offset:21504
	ds_read_b128 v[216:219], v245 offset:22528
	ds_read_b128 v[220:223], v245 offset:23552
	global_load_lds_dwordx4 v[178:179], off
	s_add_i32 m0, s63, 0x2000
	s_add_u32 s64, s56, 0x40000
	v_lshl_add_u64 v[224:225], s[56:57], 0, v[194:195]
	s_addc_u32 s65, s57, 0
	s_add_i32 s63, s66, s2
	global_load_lds_dwordx4 v[224:225], off
	v_lshl_add_u64 v[226:227], s[64:65], 0, v[198:199]
	s_mov_b32 m0, s63
	v_lshl_add_u64 v[228:229], s[58:59], 0, v[196:197]
	global_load_lds_dwordx4 v[226:227], off
	v_lshl_add_u64 v[226:227], s[64:65], 0, v[194:195]
	s_add_i32 m0, s63, 0x2000
	s_nop 0
	global_load_lds_dwordx4 v[226:227], off
	v_lshl_add_u64 v[226:227], s[58:59], 0, v[200:201]
	s_mov_b32 m0, s11
	s_nop 0
	global_load_lds_dwordx4 v[226:227], off
	s_mov_b32 m0, s20
	s_nop 0
	global_load_lds_dwordx4 v[228:229], off
	s_waitcnt vmcnt(8)
	s_waitcnt lgkmcnt(0)
	s_barrier
; #define PG8_STAGE(bufoff, gbase, voff) do { _Pragma("unroll") for (int _i = 0; _i < 2; ++_i) \
;         __builtin_amdgcn_global_load_lds((const unsigned*)((const char*)(gbase) + (voff)[_i]), (PG8_LAS unsigned*)(lds + (bufoff) + ldsw + _i * 8192), 16, 0, 0); } while (0)
; #define PG8_LDA(dst, b, h) do { _Pragma("unroll") for (int m = 0; m < 4; ++m) _Pragma("unroll") for (int k = 0; k < 2; ++k) dst[m][k] = *(const PG8_LAS bf16x8*)(lds + PG8_SA(b, h) + aoff + m * 2048 + k * 1024); } while (0)
; #define PG8_LDB(dst, b, h) do { _Pragma("unroll") for (int n = 0; n < 2; ++n) _Pragma("unroll") for (int k = 0; k < 2; ++k) dst[n][k] = *(const PG8_LAS bf16x8*)(lds + PG8_SB(b, h) + boff + n * 2048 + k * 1024); } while (0)
; #define PG8_MMA(ai, bj, At, Bt) do { __builtin_amdgcn_s_setprio(1); _Pragma("unroll") for (int m = 0; m < 4; ++m) _Pragma("unroll") for (int n = 0; n < 2; ++n) _Pragma("unroll") for (int k = 0; k < 2; ++k) \
;         acc[ai][bj][m][n] = __builtin_amdgcn_mfma_f32_16x16x32_bf16(Bt[n][k], At[m][k], acc[ai][bj][m][n], 0, 0, 0); __builtin_amdgcn_s_setprio(0); } while (0)
; #define PG8_WAIT_V(n) asm volatile("s_waitcnt vmcnt(" #n ")" ::: "memory")
; #define PG8_WAIT_L(n) asm volatile("s_waitcnt lgkmcnt(" #n ")" ::: "memory")
; #define PG8_BAR __builtin_amdgcn_s_barrier()
; #define PG8_SCHED __builtin_amdgcn_sched_barrier(0)
; template <class Epi, class Sched, bool ALIGN_EPI = false, bool SP2 = false>
; __device__ __forceinline__ void gemm_phase(PG8_LAS unsigned char* lds, const Gemm g, const Sched& S, const Epi& E) {
;     ...
;             PG8_WAIT_V(8); PG8_WAIT_L(0); PG8_BAR; PG8_MMA(1, 0, At, B0); PG8_MMA(1, 1, At, B1); PG8_BAR; PG8_SCHED;
;             PG8_LDB(B0, 1, 0); PG8_LDB(B1, 1, 1); PG8_SCHED; PG8_LDA(At, 1, 0); PG8_STAGE(PG8_SA(0, 1), a2 + hstep, voffA);
;             PG8_WAIT_V(8); PG8_WAIT_L(0); PG8_BAR; PG8_MMA(0, 0, At, B0); PG8_MMA(0, 1, At, B1); PG8_BAR; PG8_SCHED;
	v_mfma_f32_16x16x32_bf16 v[60:63], v[128:131], v[160:163], v[60:63]
	v_mfma_f32_16x16x32_bf16 v[56:59], v[136:139], v[160:163], v[56:59]
	v_mfma_f32_16x16x32_bf16 v[48:51], v[128:131], v[168:171], v[48:51]
	v_mfma_f32_16x16x32_bf16 v[40:43], v[136:139], v[168:171], v[40:43]
	v_mfma_f32_16x16x32_bf16 v[32:35], v[128:131], v[208:211], v[32:35]
	v_mfma_f32_16x16x32_bf16 v[24:27], v[136:139], v[208:211], v[24:27]
	v_mfma_f32_16x16x32_bf16 v[16:19], v[128:131], v[216:219], v[16:19]
	v_mfma_f32_16x16x32_bf16 v[8:11], v[136:139], v[216:219], v[8:11]
	v_mfma_f32_16x16x32_bf16 v[60:63], v[132:135], v[164:167], v[60:63]
	v_mfma_f32_16x16x32_bf16 v[56:59], v[140:143], v[164:167], v[56:59]
	v_mfma_f32_16x16x32_bf16 v[48:51], v[132:135], v[172:175], v[48:51]
	v_mfma_f32_16x16x32_bf16 v[40:43], v[140:143], v[172:175], v[40:43]
	v_mfma_f32_16x16x32_bf16 v[32:35], v[132:135], v[212:215], v[32:35]
	v_mfma_f32_16x16x32_bf16 v[24:27], v[140:143], v[212:215], v[24:27]
	v_mfma_f32_16x16x32_bf16 v[16:19], v[132:135], v[220:223], v[16:19]
	v_mfma_f32_16x16x32_bf16 v[8:11], v[140:143], v[220:223], v[8:11]
	v_mfma_f32_16x16x32_bf16 v[52:55], v[144:147], v[160:163], v[52:55]
	v_mfma_f32_16x16x32_bf16 v[44:47], v[152:155], v[160:163], v[44:47]
	v_mfma_f32_16x16x32_bf16 v[36:39], v[144:147], v[168:171], v[36:39]
	v_mfma_f32_16x16x32_bf16 v[28:31], v[152:155], v[168:171], v[28:31]
	v_mfma_f32_16x16x32_bf16 v[20:23], v[144:147], v[208:211], v[20:23]
	v_mfma_f32_16x16x32_bf16 v[12:15], v[152:155], v[208:211], v[12:15]
	v_mfma_f32_16x16x32_bf16 v[4:7], v[144:147], v[216:219], v[4:7]
	v_mfma_f32_16x16x32_bf16 v[0:3], v[152:155], v[216:219], v[0:3]
	v_mfma_f32_16x16x32_bf16 v[52:55], v[148:151], v[164:167], v[52:55]
	v_mfma_f32_16x16x32_bf16 v[44:47], v[156:159], v[164:167], v[44:47]
	v_mfma_f32_16x16x32_bf16 v[36:39], v[148:151], v[172:175], v[36:39]
	v_mfma_f32_16x16x32_bf16 v[28:31], v[156:159], v[172:175], v[28:31]
	v_mfma_f32_16x16x32_bf16 v[20:23], v[148:151], v[212:215], v[20:23]
	v_mfma_f32_16x16x32_bf16 v[12:15], v[156:159], v[212:215], v[12:15]
	v_mfma_f32_16x16x32_bf16 v[4:7], v[148:151], v[220:223], v[4:7]
	v_mfma_f32_16x16x32_bf16 v[0:3], v[156:159], v[220:223], v[0:3]
	s_barrier
	s_add_i32 s63, 0, 0x18000
	s_add_i32 s64, 0, 0x1c000
	v_add_u32_e32 v140, s63, v249
	v_add_u32_e32 v156, s64, v249
	ds_read_b128 v[128:131], v140
	ds_read_b128 v[132:135], v140 offset:1024
	ds_read_b128 v[136:139], v140 offset:2048
	ds_read_b128 v[140:143], v140 offset:3072
	ds_read_b128 v[144:147], v156
	ds_read_b128 v[148:151], v156 offset:1024
	ds_read_b128 v[152:155], v156 offset:2048
	ds_read_b128 v[156:159], v156 offset:3072
	s_add_u32 s58, s58, 0x40000
	s_addc_u32 s59, s59, 0
	s_mov_b32 m0, s21
	v_lshl_add_u64 v[230:231], s[58:59], 0, v[200:201]
	ds_read_b128 v[160:163], v245 offset:32768
	ds_read_b128 v[164:167], v245 offset:33792
	ds_read_b128 v[168:171], v245 offset:34816
	ds_read_b128 v[172:175], v245 offset:35840
	ds_read_b128 v[208:211], v245 offset:36864
	ds_read_b128 v[212:215], v245 offset:37888
	ds_read_b128 v[216:219], v245 offset:38912
	ds_read_b128 v[220:223], v245 offset:39936
	global_load_lds_dwordx4 v[230:231], off
	v_lshl_add_u64 v[230:231], s[58:59], 0, v[196:197]
	s_mov_b32 m0, s22
	s_nop 0
	global_load_lds_dwordx4 v[230:231], off
	s_waitcnt vmcnt(8)
	s_waitcnt lgkmcnt(0)
	s_barrier
	v_mfma_f32_16x16x32_bf16 v[124:127], v[128:131], v[160:163], v[124:127]
	v_mfma_f32_16x16x32_bf16 v[120:123], v[136:139], v[160:163], v[120:123]
	v_mfma_f32_16x16x32_bf16 v[108:111], v[128:131], v[168:171], v[108:111]
	v_mfma_f32_16x16x32_bf16 v[104:107], v[136:139], v[168:171], v[104:107]
	v_mfma_f32_16x16x32_bf16 v[92:95], v[128:131], v[208:211], v[92:95]
	v_mfma_f32_16x16x32_bf16 v[88:91], v[136:139], v[208:211], v[88:91]
	v_mfma_f32_16x16x32_bf16 v[76:79], v[128:131], v[216:219], v[76:79]
	v_mfma_f32_16x16x32_bf16 v[72:75], v[136:139], v[216:219], v[72:75]
	v_mfma_f32_16x16x32_bf16 v[124:127], v[132:135], v[164:167], v[124:127]
	v_mfma_f32_16x16x32_bf16 v[120:123], v[140:143], v[164:167], v[120:123]
	v_mfma_f32_16x16x32_bf16 v[108:111], v[132:135], v[172:175], v[108:111]
	v_mfma_f32_16x16x32_bf16 v[104:107], v[140:143], v[172:175], v[104:107]
	v_mfma_f32_16x16x32_bf16 v[92:95], v[132:135], v[212:215], v[92:95]
	v_mfma_f32_16x16x32_bf16 v[88:91], v[140:143], v[212:215], v[88:91]
	v_mfma_f32_16x16x32_bf16 v[76:79], v[132:135], v[220:223], v[76:79]
	v_mfma_f32_16x16x32_bf16 v[72:75], v[140:143], v[220:223], v[72:75]
	v_mfma_f32_16x16x32_bf16 v[116:119], v[144:147], v[160:163], v[116:119]
	v_mfma_f32_16x16x32_bf16 v[112:115], v[152:155], v[160:163], v[112:115]
	v_mfma_f32_16x16x32_bf16 v[100:103], v[144:147], v[168:171], v[100:103]
	v_mfma_f32_16x16x32_bf16 v[96:99], v[152:155], v[168:171], v[96:99]
	v_mfma_f32_16x16x32_bf16 v[84:87], v[144:147], v[208:211], v[84:87]
	v_mfma_f32_16x16x32_bf16 v[80:83], v[152:155], v[208:211], v[80:83]
	v_mfma_f32_16x16x32_bf16 v[68:71], v[144:147], v[216:219], v[68:71]
	v_mfma_f32_16x16x32_bf16 v[64:67], v[152:155], v[216:219], v[64:67]
	v_mfma_f32_16x16x32_bf16 v[116:119], v[148:151], v[164:167], v[116:119]
	v_mfma_f32_16x16x32_bf16 v[112:115], v[156:159], v[164:167], v[112:115]
	v_mfma_f32_16x16x32_bf16 v[100:103], v[148:151], v[172:175], v[100:103]
	v_mfma_f32_16x16x32_bf16 v[96:99], v[156:159], v[172:175], v[96:99]
	v_mfma_f32_16x16x32_bf16 v[84:87], v[148:151], v[212:215], v[84:87]
	v_mfma_f32_16x16x32_bf16 v[80:83], v[156:159], v[212:215], v[80:83]
	v_mfma_f32_16x16x32_bf16 v[68:71], v[148:151], v[220:223], v[68:71]
	v_mfma_f32_16x16x32_bf16 v[64:67], v[156:159], v[220:223], v[64:67]
	s_barrier
; #define PG8_STAGE(bufoff, gbase, voff) do { _Pragma("unroll") for (int _i = 0; _i < 2; ++_i) \
;         __builtin_amdgcn_global_load_lds((const unsigned*)((const char*)(gbase) + (voff)[_i]), (PG8_LAS unsigned*)(lds + (bufoff) + ldsw + _i * 8192), 16, 0, 0); } while (0)
; #define PG8_LDA(dst, b, h) do { _Pragma("unroll") for (int m = 0; m < 4; ++m) _Pragma("unroll") for (int k = 0; k < 2; ++k) dst[m][k] = *(const PG8_LAS bf16x8*)(lds + PG8_SA(b, h) + aoff + m * 2048 + k * 1024); } while (0)
; #define PG8_MMA(ai, bj, At, Bt) do { __builtin_amdgcn_s_setprio(1); _Pragma("unroll") for (int m = 0; m < 4; ++m) _Pragma("unroll") for (int n = 0; n < 2; ++n) _Pragma("unroll") for (int k = 0; k < 2; ++k) \
;         acc[ai][bj][m][n] = __builtin_amdgcn_mfma_f32_16x16x32_bf16(Bt[n][k], At[m][k], acc[ai][bj][m][n], 0, 0, 0); __builtin_amdgcn_s_setprio(0); } while (0)
; #define PG8_WAIT_V(n) asm volatile("s_waitcnt vmcnt(" #n ")" ::: "memory")
; #define PG8_WAIT_L(n) asm volatile("s_waitcnt lgkmcnt(" #n ")" ::: "memory")
; #define PG8_BAR __builtin_amdgcn_s_barrier()
; #define PG8_SCHED __builtin_amdgcn_sched_barrier(0)
; template <class Epi, class Sched, bool ALIGN_EPI = false, bool SP2 = false>
; __device__ __forceinline__ void gemm_phase(PG8_LAS unsigned char* lds, const Gemm g, const Sched& S, const Epi& E) {
;     ...
;             PG8_LDA(At, 1, 1); PG8_STAGE(PG8_SB(1, 0), b3, voffB); PG8_STAGE(PG8_SB(1, 1), b3 + hstep, voffB); PG8_STAGE(PG8_SA(1, 0), a3, voffA);
;             PG8_WAIT_V(8); PG8_WAIT_L(0); PG8_BAR; PG8_MMA(1, 0, At, B0); PG8_MMA(1, 1, At, B1); PG8_BAR; PG8_SCHED;
;     ...
;         if constexpr (ALIGN_EPI) { if (wr == 0) PG8_BAR; }
	s_add_i32 s58, s63, s2
	v_lshl_add_u64 v[178:179], v[178:179], 0, s[36:37]
	s_mov_b32 m0, s58
	ds_read_b128 v[160:163], v245 offset:49152
	ds_read_b128 v[164:167], v245 offset:50176
	ds_read_b128 v[168:171], v245 offset:51200
	ds_read_b128 v[172:175], v245 offset:52224
	ds_read_b128 v[208:211], v245 offset:53248
	ds_read_b128 v[212:215], v245 offset:54272
	ds_read_b128 v[216:219], v245 offset:55296
	ds_read_b128 v[220:223], v245 offset:56320
	global_load_lds_dwordx4 v[178:179], off
	s_add_i32 m0, s58, 0x2000
	s_add_u32 s56, s56, 0x40080
	v_lshl_add_u64 v[178:179], v[224:225], 0, s[36:37]
	s_addc_u32 s57, s57, 0
	s_add_i32 s58, s64, s2
	global_load_lds_dwordx4 v[178:179], off
	v_lshl_add_u64 v[178:179], s[56:57], 0, v[198:199]
	s_mov_b32 m0, s58
	s_nop 0
	global_load_lds_dwordx4 v[178:179], off
	v_lshl_add_u64 v[178:179], s[56:57], 0, v[194:195]
	s_add_i32 m0, s58, 0x2000
	s_nop 0
	global_load_lds_dwordx4 v[178:179], off
	v_lshl_add_u64 v[178:179], v[226:227], 0, s[36:37]
	s_mov_b32 m0, s24
	s_nop 0
	global_load_lds_dwordx4 v[178:179], off
	v_lshl_add_u64 v[178:179], v[228:229], 0, s[36:37]
	s_mov_b32 m0, s25
	s_nop 0
	global_load_lds_dwordx4 v[178:179], off
	s_waitcnt vmcnt(8)
	s_waitcnt lgkmcnt(0)
	s_barrier
	v_mfma_f32_16x16x32_bf16 v[60:63], v[128:131], v[160:163], v[60:63]
	v_mfma_f32_16x16x32_bf16 v[56:59], v[136:139], v[160:163], v[56:59]
	v_mfma_f32_16x16x32_bf16 v[48:51], v[128:131], v[168:171], v[48:51]
	v_mfma_f32_16x16x32_bf16 v[40:43], v[136:139], v[168:171], v[40:43]
	v_mfma_f32_16x16x32_bf16 v[32:35], v[128:131], v[208:211], v[32:35]
	v_mfma_f32_16x16x32_bf16 v[24:27], v[136:139], v[208:211], v[24:27]
	v_mfma_f32_16x16x32_bf16 v[16:19], v[128:131], v[216:219], v[16:19]
	v_mfma_f32_16x16x32_bf16 v[8:11], v[136:139], v[216:219], v[8:11]
	v_mfma_f32_16x16x32_bf16 v[60:63], v[132:135], v[164:167], v[60:63]
	v_mfma_f32_16x16x32_bf16 v[56:59], v[140:143], v[164:167], v[56:59]
	v_mfma_f32_16x16x32_bf16 v[48:51], v[132:135], v[172:175], v[48:51]
	v_mfma_f32_16x16x32_bf16 v[40:43], v[140:143], v[172:175], v[40:43]
	v_mfma_f32_16x16x32_bf16 v[32:35], v[132:135], v[212:215], v[32:35]
	v_mfma_f32_16x16x32_bf16 v[24:27], v[140:143], v[212:215], v[24:27]
	v_mfma_f32_16x16x32_bf16 v[16:19], v[132:135], v[220:223], v[16:19]
	v_mfma_f32_16x16x32_bf16 v[8:11], v[140:143], v[220:223], v[8:11]
	v_mfma_f32_16x16x32_bf16 v[52:55], v[144:147], v[160:163], v[52:55]
	v_mfma_f32_16x16x32_bf16 v[44:47], v[152:155], v[160:163], v[44:47]
	v_mfma_f32_16x16x32_bf16 v[36:39], v[144:147], v[168:171], v[36:39]
	v_mfma_f32_16x16x32_bf16 v[28:31], v[152:155], v[168:171], v[28:31]
	v_mfma_f32_16x16x32_bf16 v[20:23], v[144:147], v[208:211], v[20:23]
	v_mfma_f32_16x16x32_bf16 v[12:15], v[152:155], v[208:211], v[12:15]
	v_mfma_f32_16x16x32_bf16 v[4:7], v[144:147], v[216:219], v[4:7]
	v_mfma_f32_16x16x32_bf16 v[0:3], v[152:155], v[216:219], v[0:3]
	v_mfma_f32_16x16x32_bf16 v[52:55], v[148:151], v[164:167], v[52:55]
	v_mfma_f32_16x16x32_bf16 v[44:47], v[156:159], v[164:167], v[44:47]
	v_mfma_f32_16x16x32_bf16 v[36:39], v[148:151], v[172:175], v[36:39]
	v_mfma_f32_16x16x32_bf16 v[28:31], v[156:159], v[172:175], v[28:31]
	v_mfma_f32_16x16x32_bf16 v[20:23], v[148:151], v[212:215], v[20:23]
	v_mfma_f32_16x16x32_bf16 v[12:15], v[156:159], v[212:215], v[12:15]
	v_mfma_f32_16x16x32_bf16 v[4:7], v[148:151], v[220:223], v[4:7]
	v_mfma_f32_16x16x32_bf16 v[0:3], v[156:159], v[220:223], v[0:3]
	s_barrier
	s_add_i32 s62, s62, 2
	s_add_u32 s49, s49, 0x100
	s_addc_u32 s51, s51, 0
	s_add_u32 s4, s4, 0x100
	s_addc_u32 s5, s5, 0
	s_cmp_gt_u32 s62, 13
	s_cbranch_scc0 .LBB0_143
	s_and_b64 vcc, exec, s[44:45]
	s_cbranch_vccz .LBB0_146
	s_barrier

; #define PG8_STAGE(bufoff, gbase, voff) do { _Pragma("unroll") for (int _i = 0; _i < 2; ++_i) \
;         __builtin_amdgcn_global_load_lds((const unsigned*)((const char*)(gbase) + (voff)[_i]), (PG8_LAS unsigned*)(lds + (bufoff) + ldsw + _i * 8192), 16, 0, 0); } while (0)
; #define PG8_LDA(dst, b, h) do { _Pragma("unroll") for (int m = 0; m < 4; ++m) _Pragma("unroll") for (int k = 0; k < 2; ++k) dst[m][k] = *(const PG8_LAS bf16x8*)(lds + PG8_SA(b, h) + aoff + m * 2048 + k * 1024); } while (0)
; #define PG8_LDB(dst, b, h) do { _Pragma("unroll") for (int n = 0; n < 2; ++n) _Pragma("unroll") for (int k = 0; k < 2; ++k) dst[n][k] = *(const PG8_LAS bf16x8*)(lds + PG8_SB(b, h) + boff + n * 2048 + k * 1024); } while (0)
; #define PG8_MMA(ai, bj, At, Bt) do { __builtin_amdgcn_s_setprio(1); _Pragma("unroll") for (int m = 0; m < 4; ++m) _Pragma("unroll") for (int n = 0; n < 2; ++n) _Pragma("unroll") for (int k = 0; k < 2; ++k) \
;         acc[ai][bj][m][n] = __builtin_amdgcn_mfma_f32_16x16x32_bf16(Bt[n][k], At[m][k], acc[ai][bj][m][n], 0, 0, 0); __builtin_amdgcn_s_setprio(0); } while (0)
; #define PG8_WAIT_V(n) asm volatile("s_waitcnt vmcnt(" #n ")" ::: "memory")
; #define PG8_WAIT_L(n) asm volatile("s_waitcnt lgkmcnt(" #n ")" ::: "memory")
; template <class Epi, class Sched, bool ALIGN_EPI = false, bool SP2 = false>
; __device__ __forceinline__ void gemm_phase(PG8_LAS unsigned char* lds, const Gemm g, const Sched& S, const Epi& E) {
;     ...
;             const bool last = (t == nt - 2);
;             const char* a1 = cA + (size_t)(t + 1) * kstep;
;             const char* a2 = last ? nA : cA + (size_t)(t + 2) * kstep; const char* b2 = last ? nB : cB + (size_t)(t + 2) * kstep;
;             const char* a3 = a2 + kstep; const char* b3 = b2 + kstep;
;             if (last && has_next) S.a_ready(nxt);
;             if constexpr (SP2) {
;             PG8_LDB(B0, 0, 0); PG8_LDB(B1, 0, 1); PG8_SCHED; PG8_LDA(At, 0, 0); PG8_STAGE(PG8_SA(1, 1), a1 + hstep, voffA);
;             PG8_WAIT_V(8); PG8_WAIT_L(0); PG8_BAR; PG8_MMA(0, 0, At, B0); PG8_MMA(0, 1, At, B1); PG8_BAR; PG8_SCHED;
;             PG8_LDA(At, 0, 1); PG8_STAGE(PG8_SB(0, 0), b2, voffB); PG8_STAGE(PG8_SB(0, 1), b2 + hstep, voffB); PG8_STAGE(PG8_SA(0, 0), a2, voffA);
;             PG8_WAIT_V(8); PG8_WAIT_L(0); PG8_BAR; PG8_MMA(1, 0, At, B0); PG8_MMA(1, 1, At, B1); PG8_BAR; PG8_SCHED;
.LBB0_265:
	s_add_u32 s16, s0, 0xfffc0080
	s_addc_u32 s17, s1, -1
	s_add_i32 s25, 0, 0x10000
	s_cmp_eq_u32 s24, 12
	s_cselect_b32 s27, s11, s17
	s_cselect_b32 s26, s14, s16
	v_add_u32_e32 v146, s25, v149
	s_cselect_b32 s17, s20, s23
	s_cselect_b32 s16, s21, s22
	s_add_i32 s30, 0, 0x14000
	ds_read_b128 v[142:145], v146
	ds_read_b128 v[154:157], v146 offset:1024
	ds_read_b128 v[158:161], v146 offset:2048
	ds_read_b128 v[162:165], v146 offset:3072
	v_add_u32_e32 v146, s30, v149
	ds_read_b128 v[166:169], v146
	ds_read_b128 v[170:173], v146 offset:1024
	ds_read_b128 v[194:197], v146 offset:2048
	ds_read_b128 v[198:201], v146 offset:3072
	v_lshl_add_u64 v[146:147], s[0:1], 0, v[140:141]
	s_add_i32 m0, s54, 0xc000
	ds_read_b128 v[202:205], v153
	ds_read_b128 v[206:209], v153 offset:1024
	ds_read_b128 v[210:213], v153 offset:2048
	ds_read_b128 v[214:217], v153 offset:3072
	ds_read_b128 v[218:221], v153 offset:4096
	ds_read_b128 v[222:225], v153 offset:5120
	ds_read_b128 v[226:229], v153 offset:6144
	ds_read_b128 v[230:233], v153 offset:7168
	global_load_lds_dwordx4 v[146:147], off
	v_lshl_add_u64 v[146:147], s[0:1], 0, v[138:139]
	s_add_i32 m0, s54, 0xe000
	s_nop 0
	global_load_lds_dwordx4 v[146:147], off
	s_waitcnt vmcnt(8)
	s_waitcnt lgkmcnt(0)
	s_barrier
	v_mfma_f32_16x16x32_bf16 v[124:127], v[142:145], v[202:205], v[124:127]
	v_mfma_f32_16x16x32_bf16 v[120:123], v[158:161], v[202:205], v[120:123]
	v_mfma_f32_16x16x32_bf16 v[108:111], v[142:145], v[210:213], v[108:111]
	v_mfma_f32_16x16x32_bf16 v[104:107], v[158:161], v[210:213], v[104:107]
	v_mfma_f32_16x16x32_bf16 v[92:95], v[142:145], v[218:221], v[92:95]
	v_mfma_f32_16x16x32_bf16 v[88:91], v[158:161], v[218:221], v[88:91]
	v_mfma_f32_16x16x32_bf16 v[76:79], v[142:145], v[226:229], v[76:79]
	v_mfma_f32_16x16x32_bf16 v[72:75], v[158:161], v[226:229], v[72:75]
	v_mfma_f32_16x16x32_bf16 v[124:127], v[154:157], v[206:209], v[124:127]
	v_mfma_f32_16x16x32_bf16 v[120:123], v[162:165], v[206:209], v[120:123]
	v_mfma_f32_16x16x32_bf16 v[108:111], v[154:157], v[214:217], v[108:111]
	v_mfma_f32_16x16x32_bf16 v[104:107], v[162:165], v[214:217], v[104:107]
	v_mfma_f32_16x16x32_bf16 v[92:95], v[154:157], v[222:225], v[92:95]
	v_mfma_f32_16x16x32_bf16 v[88:91], v[162:165], v[222:225], v[88:91]
	v_mfma_f32_16x16x32_bf16 v[76:79], v[154:157], v[230:233], v[76:79]
	v_mfma_f32_16x16x32_bf16 v[72:75], v[162:165], v[230:233], v[72:75]
	v_mfma_f32_16x16x32_bf16 v[116:119], v[166:169], v[202:205], v[116:119]
	v_mfma_f32_16x16x32_bf16 v[112:115], v[194:197], v[202:205], v[112:115]
	v_mfma_f32_16x16x32_bf16 v[100:103], v[166:169], v[210:213], v[100:103]
	v_mfma_f32_16x16x32_bf16 v[96:99], v[194:197], v[210:213], v[96:99]
	v_mfma_f32_16x16x32_bf16 v[84:87], v[166:169], v[218:221], v[84:87]
	v_mfma_f32_16x16x32_bf16 v[80:83], v[194:197], v[218:221], v[80:83]
	v_mfma_f32_16x16x32_bf16 v[68:71], v[166:169], v[226:229], v[68:71]
	v_mfma_f32_16x16x32_bf16 v[64:67], v[194:197], v[226:229], v[64:67]
	v_mfma_f32_16x16x32_bf16 v[116:119], v[170:173], v[206:209], v[116:119]
	v_mfma_f32_16x16x32_bf16 v[112:115], v[198:201], v[206:209], v[112:115]
	v_mfma_f32_16x16x32_bf16 v[100:103], v[170:173], v[214:217], v[100:103]
	v_mfma_f32_16x16x32_bf16 v[96:99], v[198:201], v[214:217], v[96:99]
	v_mfma_f32_16x16x32_bf16 v[84:87], v[170:173], v[222:225], v[84:87]
	v_mfma_f32_16x16x32_bf16 v[80:83], v[198:201], v[222:225], v[80:83]
	v_mfma_f32_16x16x32_bf16 v[68:71], v[170:173], v[230:233], v[68:71]
	v_mfma_f32_16x16x32_bf16 v[64:67], v[198:201], v[230:233], v[64:67]
	s_barrier
	s_add_i32 s25, s25, s2
	v_lshl_add_u64 v[146:147], s[16:17], 0, v[132:133]
	s_mov_b32 m0, s25
	ds_read_b128 v[202:205], v153 offset:16384
	ds_read_b128 v[206:209], v153 offset:17408
	ds_read_b128 v[210:213], v153 offset:18432
	ds_read_b128 v[214:217], v153 offset:19456
	ds_read_b128 v[218:221], v153 offset:20480
	ds_read_b128 v[222:225], v153 offset:21504
	ds_read_b128 v[226:229], v153 offset:22528
	ds_read_b128 v[230:233], v153 offset:23552
	global_load_lds_dwordx4 v[146:147], off
	s_add_i32 m0, s25, 0x2000
	s_add_u32 s28, s16, 0x40000
	v_lshl_add_u64 v[174:175], s[16:17], 0, v[128:129]
	s_addc_u32 s29, s17, 0
	s_add_i32 s25, s30, s2
	global_load_lds_dwordx4 v[174:175], off
	v_lshl_add_u64 v[178:179], s[28:29], 0, v[132:133]
	s_mov_b32 m0, s25
	v_lshl_add_u64 v[234:235], s[26:27], 0, v[130:131]
	global_load_lds_dwordx4 v[178:179], off
	v_lshl_add_u64 v[178:179], s[28:29], 0, v[128:129]
	s_add_i32 m0, s25, 0x2000
	s_nop 0
	global_load_lds_dwordx4 v[178:179], off
	v_lshl_add_u64 v[178:179], s[26:27], 0, v[134:135]
	s_mov_b32 m0, s54
	s_nop 0
	global_load_lds_dwordx4 v[178:179], off
	s_mov_b32 m0, s55
	s_nop 0
	global_load_lds_dwordx4 v[234:235], off
	s_waitcnt vmcnt(8)
	s_waitcnt lgkmcnt(0)
	s_barrier
; #define PG8_STAGE(bufoff, gbase, voff) do { _Pragma("unroll") for (int _i = 0; _i < 2; ++_i) \
;         __builtin_amdgcn_global_load_lds((const unsigned*)((const char*)(gbase) + (voff)[_i]), (PG8_LAS unsigned*)(lds + (bufoff) + ldsw + _i * 8192), 16, 0, 0); } while (0)
; #define PG8_LDA(dst, b, h) do { _Pragma("unroll") for (int m = 0; m < 4; ++m) _Pragma("unroll") for (int k = 0; k < 2; ++k) dst[m][k] = *(const PG8_LAS bf16x8*)(lds + PG8_SA(b, h) + aoff + m * 2048 + k * 1024); } while (0)
; #define PG8_LDB(dst, b, h) do { _Pragma("unroll") for (int n = 0; n < 2; ++n) _Pragma("unroll") for (int k = 0; k < 2; ++k) dst[n][k] = *(const PG8_LAS bf16x8*)(lds + PG8_SB(b, h) + boff + n * 2048 + k * 1024); } while (0)
; #define PG8_MMA(ai, bj, At, Bt) do { __builtin_amdgcn_s_setprio(1); _Pragma("unroll") for (int m = 0; m < 4; ++m) _Pragma("unroll") for (int n = 0; n < 2; ++n) _Pragma("unroll") for (int k = 0; k < 2; ++k) \
;         acc[ai][bj][m][n] = __builtin_amdgcn_mfma_f32_16x16x32_bf16(Bt[n][k], At[m][k], acc[ai][bj][m][n], 0, 0, 0); __builtin_amdgcn_s_setprio(0); } while (0)
; #define PG8_WAIT_V(n) asm volatile("s_waitcnt vmcnt(" #n ")" ::: "memory")
; #define PG8_WAIT_L(n) asm volatile("s_waitcnt lgkmcnt(" #n ")" ::: "memory")
; #define PG8_BAR __builtin_amdgcn_s_barrier()
; #define PG8_SCHED __builtin_amdgcn_sched_barrier(0)
; template <class Epi, class Sched, bool ALIGN_EPI = false, bool SP2 = false>
; __device__ __forceinline__ void gemm_phase(PG8_LAS unsigned char* lds, const Gemm g, const Sched& S, const Epi& E) {
;     ...
;             PG8_WAIT_V(8); PG8_WAIT_L(0); PG8_BAR; PG8_MMA(1, 0, At, B0); PG8_MMA(1, 1, At, B1); PG8_BAR; PG8_SCHED;
;             PG8_LDB(B0, 1, 0); PG8_LDB(B1, 1, 1); PG8_SCHED; PG8_LDA(At, 1, 0); PG8_STAGE(PG8_SA(0, 1), a2 + hstep, voffA);
;             PG8_WAIT_V(8); PG8_WAIT_L(0); PG8_BAR; PG8_MMA(0, 0, At, B0); PG8_MMA(0, 1, At, B1); PG8_BAR; PG8_SCHED;
	v_mfma_f32_16x16x32_bf16 v[60:63], v[142:145], v[202:205], v[60:63]
	v_mfma_f32_16x16x32_bf16 v[56:59], v[158:161], v[202:205], v[56:59]
	v_mfma_f32_16x16x32_bf16 v[44:47], v[142:145], v[210:213], v[44:47]
	v_mfma_f32_16x16x32_bf16 v[40:43], v[158:161], v[210:213], v[40:43]
	v_mfma_f32_16x16x32_bf16 v[28:31], v[142:145], v[218:221], v[28:31]
	v_mfma_f32_16x16x32_bf16 v[24:27], v[158:161], v[218:221], v[24:27]
	v_mfma_f32_16x16x32_bf16 v[12:15], v[142:145], v[226:229], v[12:15]
	v_mfma_f32_16x16x32_bf16 v[8:11], v[158:161], v[226:229], v[8:11]
	v_mfma_f32_16x16x32_bf16 v[60:63], v[154:157], v[206:209], v[60:63]
	v_mfma_f32_16x16x32_bf16 v[56:59], v[162:165], v[206:209], v[56:59]
	v_mfma_f32_16x16x32_bf16 v[44:47], v[154:157], v[214:217], v[44:47]
	v_mfma_f32_16x16x32_bf16 v[40:43], v[162:165], v[214:217], v[40:43]
	v_mfma_f32_16x16x32_bf16 v[28:31], v[154:157], v[222:225], v[28:31]
	v_mfma_f32_16x16x32_bf16 v[24:27], v[162:165], v[222:225], v[24:27]
	v_mfma_f32_16x16x32_bf16 v[12:15], v[154:157], v[230:233], v[12:15]
	v_mfma_f32_16x16x32_bf16 v[8:11], v[162:165], v[230:233], v[8:11]
	v_mfma_f32_16x16x32_bf16 v[52:55], v[166:169], v[202:205], v[52:55]
	v_mfma_f32_16x16x32_bf16 v[48:51], v[194:197], v[202:205], v[48:51]
	v_mfma_f32_16x16x32_bf16 v[36:39], v[166:169], v[210:213], v[36:39]
	v_mfma_f32_16x16x32_bf16 v[32:35], v[194:197], v[210:213], v[32:35]
	v_mfma_f32_16x16x32_bf16 v[20:23], v[166:169], v[218:221], v[20:23]
	v_mfma_f32_16x16x32_bf16 v[16:19], v[194:197], v[218:221], v[16:19]
	v_mfma_f32_16x16x32_bf16 v[4:7], v[166:169], v[226:229], v[4:7]
	v_mfma_f32_16x16x32_bf16 v[0:3], v[194:197], v[226:229], v[0:3]
	v_mfma_f32_16x16x32_bf16 v[52:55], v[170:173], v[206:209], v[52:55]
	v_mfma_f32_16x16x32_bf16 v[48:51], v[198:201], v[206:209], v[48:51]
	v_mfma_f32_16x16x32_bf16 v[36:39], v[170:173], v[214:217], v[36:39]
	v_mfma_f32_16x16x32_bf16 v[32:35], v[198:201], v[214:217], v[32:35]
	v_mfma_f32_16x16x32_bf16 v[20:23], v[170:173], v[222:225], v[20:23]
	v_mfma_f32_16x16x32_bf16 v[16:19], v[198:201], v[222:225], v[16:19]
	v_mfma_f32_16x16x32_bf16 v[4:7], v[170:173], v[230:233], v[4:7]
	v_mfma_f32_16x16x32_bf16 v[0:3], v[198:201], v[230:233], v[0:3]
	s_barrier
	s_add_i32 s25, 0, 0x18000
	v_add_u32_e32 v148, s25, v149
	s_add_i32 s28, 0, 0x1c000
	ds_read_b128 v[142:145], v148
	ds_read_b128 v[154:157], v148 offset:1024
	ds_read_b128 v[158:161], v148 offset:2048
	ds_read_b128 v[162:165], v148 offset:3072
	v_add_u32_e32 v148, s28, v149
	ds_read_b128 v[166:169], v148
	ds_read_b128 v[170:173], v148 offset:1024
	ds_read_b128 v[194:197], v148 offset:2048
	ds_read_b128 v[198:201], v148 offset:3072
	s_add_u32 s26, s26, 0x40000
	s_addc_u32 s27, s27, 0
	s_mov_b32 m0, s56
	v_lshl_add_u64 v[236:237], s[26:27], 0, v[134:135]
	ds_read_b128 v[202:205], v153 offset:32768
	ds_read_b128 v[206:209], v153 offset:33792
	ds_read_b128 v[210:213], v153 offset:34816
	ds_read_b128 v[214:217], v153 offset:35840
	ds_read_b128 v[218:221], v153 offset:36864
	ds_read_b128 v[222:225], v153 offset:37888
	ds_read_b128 v[226:229], v153 offset:38912
	ds_read_b128 v[230:233], v153 offset:39936
	global_load_lds_dwordx4 v[236:237], off
	v_lshl_add_u64 v[236:237], s[26:27], 0, v[130:131]
	s_mov_b32 m0, s57
	s_nop 0
	global_load_lds_dwordx4 v[236:237], off
	s_waitcnt vmcnt(8)
	s_waitcnt lgkmcnt(0)
	s_barrier
	v_mfma_f32_16x16x32_bf16 v[124:127], v[142:145], v[202:205], v[124:127]
	v_mfma_f32_16x16x32_bf16 v[120:123], v[158:161], v[202:205], v[120:123]
	v_mfma_f32_16x16x32_bf16 v[108:111], v[142:145], v[210:213], v[108:111]
	v_mfma_f32_16x16x32_bf16 v[104:107], v[158:161], v[210:213], v[104:107]
	v_mfma_f32_16x16x32_bf16 v[92:95], v[142:145], v[218:221], v[92:95]
	v_mfma_f32_16x16x32_bf16 v[88:91], v[158:161], v[218:221], v[88:91]
	v_mfma_f32_16x16x32_bf16 v[76:79], v[142:145], v[226:229], v[76:79]
	v_mfma_f32_16x16x32_bf16 v[72:75], v[158:161], v[226:229], v[72:75]
	v_mfma_f32_16x16x32_bf16 v[124:127], v[154:157], v[206:209], v[124:127]
	v_mfma_f32_16x16x32_bf16 v[120:123], v[162:165], v[206:209], v[120:123]
	v_mfma_f32_16x16x32_bf16 v[108:111], v[154:157], v[214:217], v[108:111]
	v_mfma_f32_16x16x32_bf16 v[104:107], v[162:165], v[214:217], v[104:107]
	v_mfma_f32_16x16x32_bf16 v[92:95], v[154:157], v[222:225], v[92:95]
	v_mfma_f32_16x16x32_bf16 v[88:91], v[162:165], v[222:225], v[88:91]
	v_mfma_f32_16x16x32_bf16 v[76:79], v[154:157], v[230:233], v[76:79]
	v_mfma_f32_16x16x32_bf16 v[72:75], v[162:165], v[230:233], v[72:75]
	v_mfma_f32_16x16x32_bf16 v[116:119], v[166:169], v[202:205], v[116:119]
	v_mfma_f32_16x16x32_bf16 v[112:115], v[194:197], v[202:205], v[112:115]
	v_mfma_f32_16x16x32_bf16 v[100:103], v[166:169], v[210:213], v[100:103]
	v_mfma_f32_16x16x32_bf16 v[96:99], v[194:197], v[210:213], v[96:99]
	v_mfma_f32_16x16x32_bf16 v[84:87], v[166:169], v[218:221], v[84:87]
	v_mfma_f32_16x16x32_bf16 v[80:83], v[194:197], v[218:221], v[80:83]
	v_mfma_f32_16x16x32_bf16 v[68:71], v[166:169], v[226:229], v[68:71]
	v_mfma_f32_16x16x32_bf16 v[64:67], v[194:197], v[226:229], v[64:67]
	v_mfma_f32_16x16x32_bf16 v[116:119], v[170:173], v[206:209], v[116:119]
	v_mfma_f32_16x16x32_bf16 v[112:115], v[198:201], v[206:209], v[112:115]
	v_mfma_f32_16x16x32_bf16 v[100:103], v[170:173], v[214:217], v[100:103]
	v_mfma_f32_16x16x32_bf16 v[96:99], v[198:201], v[214:217], v[96:99]
	v_mfma_f32_16x16x32_bf16 v[84:87], v[170:173], v[222:225], v[84:87]
	v_mfma_f32_16x16x32_bf16 v[80:83], v[198:201], v[222:225], v[80:83]
	v_mfma_f32_16x16x32_bf16 v[68:71], v[170:173], v[230:233], v[68:71]
	v_mfma_f32_16x16x32_bf16 v[64:67], v[198:201], v[230:233], v[64:67]
	s_barrier
; #define PG8_STAGE(bufoff, gbase, voff) do { _Pragma("unroll") for (int _i = 0; _i < 2; ++_i) \
;         __builtin_amdgcn_global_load_lds((const unsigned*)((const char*)(gbase) + (voff)[_i]), (PG8_LAS unsigned*)(lds + (bufoff) + ldsw + _i * 8192), 16, 0, 0); } while (0)
; #define PG8_LDA(dst, b, h) do { _Pragma("unroll") for (int m = 0; m < 4; ++m) _Pragma("unroll") for (int k = 0; k < 2; ++k) dst[m][k] = *(const PG8_LAS bf16x8*)(lds + PG8_SA(b, h) + aoff + m * 2048 + k * 1024); } while (0)
; #define PG8_MMA(ai, bj, At, Bt) do { __builtin_amdgcn_s_setprio(1); _Pragma("unroll") for (int m = 0; m < 4; ++m) _Pragma("unroll") for (int n = 0; n < 2; ++n) _Pragma("unroll") for (int k = 0; k < 2; ++k) \
;         acc[ai][bj][m][n] = __builtin_amdgcn_mfma_f32_16x16x32_bf16(Bt[n][k], At[m][k], acc[ai][bj][m][n], 0, 0, 0); __builtin_amdgcn_s_setprio(0); } while (0)
; #define PG8_WAIT_V(n) asm volatile("s_waitcnt vmcnt(" #n ")" ::: "memory")
; #define PG8_WAIT_L(n) asm volatile("s_waitcnt lgkmcnt(" #n ")" ::: "memory")
; #define PG8_BAR __builtin_amdgcn_s_barrier()
; #define PG8_SCHED __builtin_amdgcn_sched_barrier(0)
; template <class Epi, class Sched, bool ALIGN_EPI = false, bool SP2 = false>
; __device__ __forceinline__ void gemm_phase(PG8_LAS unsigned char* lds, const Gemm g, const Sched& S, const Epi& E) {
;     ...
;             PG8_LDA(At, 1, 1); PG8_STAGE(PG8_SB(1, 0), b3, voffB); PG8_STAGE(PG8_SB(1, 1), b3 + hstep, voffB); PG8_STAGE(PG8_SA(1, 0), a3, voffA);
;             PG8_WAIT_V(8); PG8_WAIT_L(0); PG8_BAR; PG8_MMA(1, 0, At, B0); PG8_MMA(1, 1, At, B1); PG8_BAR; PG8_SCHED;
;     ...
;         if constexpr (ALIGN_EPI) { if (wr == 0) PG8_BAR; }
	s_add_i32 s25, s25, s2
	v_lshl_add_u64 v[146:147], v[146:147], 0, s[36:37]
	s_mov_b32 m0, s25
	ds_read_b128 v[202:205], v153 offset:49152
	ds_read_b128 v[206:209], v153 offset:50176
	ds_read_b128 v[210:213], v153 offset:51200
	ds_read_b128 v[214:217], v153 offset:52224
	ds_read_b128 v[218:221], v153 offset:53248
	ds_read_b128 v[222:225], v153 offset:54272
	ds_read_b128 v[226:229], v153 offset:55296
	ds_read_b128 v[230:233], v153 offset:56320
	global_load_lds_dwordx4 v[146:147], off
	s_add_i32 m0, s25, 0x2000
	s_add_u32 s16, s16, 0x40080
	v_lshl_add_u64 v[146:147], v[174:175], 0, s[36:37]
	s_addc_u32 s17, s17, 0
	s_add_i32 s25, s28, s2
	global_load_lds_dwordx4 v[146:147], off
	v_lshl_add_u64 v[146:147], s[16:17], 0, v[132:133]
	s_mov_b32 m0, s25
	s_nop 0
	global_load_lds_dwordx4 v[146:147], off
	v_lshl_add_u64 v[146:147], s[16:17], 0, v[128:129]
	s_add_i32 m0, s25, 0x2000
	s_nop 0
	global_load_lds_dwordx4 v[146:147], off
	v_lshl_add_u64 v[146:147], v[178:179], 0, s[36:37]
	s_mov_b32 m0, s59
	s_nop 0
	global_load_lds_dwordx4 v[146:147], off
	v_lshl_add_u64 v[146:147], v[234:235], 0, s[36:37]
	s_mov_b32 m0, s62
	s_nop 0
	global_load_lds_dwordx4 v[146:147], off
	s_waitcnt vmcnt(8)
	s_waitcnt lgkmcnt(0)
	s_barrier
	v_mfma_f32_16x16x32_bf16 v[60:63], v[142:145], v[202:205], v[60:63]
	v_mfma_f32_16x16x32_bf16 v[56:59], v[158:161], v[202:205], v[56:59]
	v_mfma_f32_16x16x32_bf16 v[44:47], v[142:145], v[210:213], v[44:47]
	v_mfma_f32_16x16x32_bf16 v[40:43], v[158:161], v[210:213], v[40:43]
	v_mfma_f32_16x16x32_bf16 v[28:31], v[142:145], v[218:221], v[28:31]
	v_mfma_f32_16x16x32_bf16 v[24:27], v[158:161], v[218:221], v[24:27]
	v_mfma_f32_16x16x32_bf16 v[12:15], v[142:145], v[226:229], v[12:15]
	v_mfma_f32_16x16x32_bf16 v[8:11], v[158:161], v[226:229], v[8:11]
	v_mfma_f32_16x16x32_bf16 v[60:63], v[154:157], v[206:209], v[60:63]
	v_mfma_f32_16x16x32_bf16 v[56:59], v[162:165], v[206:209], v[56:59]
	v_mfma_f32_16x16x32_bf16 v[44:47], v[154:157], v[214:217], v[44:47]
	v_mfma_f32_16x16x32_bf16 v[40:43], v[162:165], v[214:217], v[40:43]
	v_mfma_f32_16x16x32_bf16 v[28:31], v[154:157], v[222:225], v[28:31]
	v_mfma_f32_16x16x32_bf16 v[24:27], v[162:165], v[222:225], v[24:27]
	v_mfma_f32_16x16x32_bf16 v[12:15], v[154:157], v[230:233], v[12:15]
	v_mfma_f32_16x16x32_bf16 v[8:11], v[162:165], v[230:233], v[8:11]
	v_mfma_f32_16x16x32_bf16 v[52:55], v[166:169], v[202:205], v[52:55]
	v_mfma_f32_16x16x32_bf16 v[48:51], v[194:197], v[202:205], v[48:51]
	v_mfma_f32_16x16x32_bf16 v[36:39], v[166:169], v[210:213], v[36:39]
	v_mfma_f32_16x16x32_bf16 v[32:35], v[194:197], v[210:213], v[32:35]
	v_mfma_f32_16x16x32_bf16 v[20:23], v[166:169], v[218:221], v[20:23]
	v_mfma_f32_16x16x32_bf16 v[16:19], v[194:197], v[218:221], v[16:19]
	v_mfma_f32_16x16x32_bf16 v[4:7], v[166:169], v[226:229], v[4:7]
	v_mfma_f32_16x16x32_bf16 v[0:3], v[194:197], v[226:229], v[0:3]
	v_mfma_f32_16x16x32_bf16 v[52:55], v[170:173], v[206:209], v[52:55]
	v_mfma_f32_16x16x32_bf16 v[48:51], v[198:201], v[206:209], v[48:51]
	v_mfma_f32_16x16x32_bf16 v[36:39], v[170:173], v[214:217], v[36:39]
	v_mfma_f32_16x16x32_bf16 v[32:35], v[198:201], v[214:217], v[32:35]
	v_mfma_f32_16x16x32_bf16 v[20:23], v[170:173], v[222:225], v[20:23]
	v_mfma_f32_16x16x32_bf16 v[16:19], v[198:201], v[222:225], v[16:19]
	v_mfma_f32_16x16x32_bf16 v[4:7], v[170:173], v[230:233], v[4:7]
	v_mfma_f32_16x16x32_bf16 v[0:3], v[198:201], v[230:233], v[0:3]
	s_barrier
	s_add_i32 s24, s24, 2
	s_add_u32 s22, s22, 0x100
	s_addc_u32 s23, s23, 0
	s_add_u32 s0, s0, 0x100
	s_addc_u32 s1, s1, 0
	s_cmp_gt_u32 s24, 13
	s_cbranch_scc0 .LBB0_265
	s_and_b64 vcc, exec, s[44:45]
	s_cbranch_vccz .LBB0_268
	s_barrier

; #define PG8_STAGE(bufoff, gbase, voff) do { _Pragma("unroll") for (int _i = 0; _i < 2; ++_i) \
;         __builtin_amdgcn_global_load_lds((const unsigned*)((const char*)(gbase) + (voff)[_i]), (PG8_LAS unsigned*)(lds + (bufoff) + ldsw + _i * 8192), 16, 0, 0); } while (0)
; #define PG8_LDA(dst, b, h) do { _Pragma("unroll") for (int m = 0; m < 4; ++m) _Pragma("unroll") for (int k = 0; k < 2; ++k) dst[m][k] = *(const PG8_LAS bf16x8*)(lds + PG8_SA(b, h) + aoff + m * 2048 + k * 1024); } while (0)
; #define PG8_LDB(dst, b, h) do { _Pragma("unroll") for (int n = 0; n < 2; ++n) _Pragma("unroll") for (int k = 0; k < 2; ++k) dst[n][k] = *(const PG8_LAS bf16x8*)(lds + PG8_SB(b, h) + boff + n * 2048 + k * 1024); } while (0)
; #define PG8_MMA(ai, bj, At, Bt) do { __builtin_amdgcn_s_setprio(1); _Pragma("unroll") for (int m = 0; m < 4; ++m) _Pragma("unroll") for (int n = 0; n < 2; ++n) _Pragma("unroll") for (int k = 0; k < 2; ++k) \
;         acc[ai][bj][m][n] = __builtin_amdgcn_mfma_f32_16x16x32_bf16(Bt[n][k], At[m][k], acc[ai][bj][m][n], 0, 0, 0); __builtin_amdgcn_s_setprio(0); } while (0)
; #define PG8_WAIT_V(n) asm volatile("s_waitcnt vmcnt(" #n ")" ::: "memory")
; #define PG8_WAIT_L(n) asm volatile("s_waitcnt lgkmcnt(" #n ")" ::: "memory")
; template <class Epi, class Sched, bool ALIGN_EPI = false, bool SP2 = false>
; __device__ __forceinline__ void gemm_phase(PG8_LAS unsigned char* lds, const Gemm g, const Sched& S, const Epi& E) {
;     ...
;             const bool last = (t == nt - 2);
;             const char* a1 = cA + (size_t)(t + 1) * kstep;
;             const char* a2 = last ? nA : cA + (size_t)(t + 2) * kstep; const char* b2 = last ? nB : cB + (size_t)(t + 2) * kstep;
;             const char* a3 = a2 + kstep; const char* b3 = b2 + kstep;
;             if (last && has_next) S.a_ready(nxt);
;             if constexpr (SP2) {
;             PG8_LDB(B0, 0, 0); PG8_LDB(B1, 0, 1); PG8_SCHED; PG8_LDA(At, 0, 0); PG8_STAGE(PG8_SA(1, 1), a1 + hstep, voffA);
;             PG8_WAIT_V(8); PG8_WAIT_L(0); PG8_BAR; PG8_MMA(0, 0, At, B0); PG8_MMA(0, 1, At, B1); PG8_BAR; PG8_SCHED;
;             PG8_LDA(At, 0, 1); PG8_STAGE(PG8_SB(0, 0), b2, voffB); PG8_STAGE(PG8_SB(0, 1), b2 + hstep, voffB); PG8_STAGE(PG8_SA(0, 0), a2, voffA);
;             PG8_WAIT_V(8); PG8_WAIT_L(0); PG8_BAR; PG8_MMA(1, 0, At, B0); PG8_MMA(1, 1, At, B1); PG8_BAR; PG8_SCHED;
.LBB0_558:
	s_add_u32 s50, s48, 0xfffc0080
	s_addc_u32 s51, s49, -1
	s_add_i32 s56, 0, 0x10000
	s_cmp_eq_u32 s55, 12
	s_cselect_b32 s53, s33, s51
	s_cselect_b32 s52, s34, s50
	s_cselect_b32 s51, s35, s54
	s_cselect_b32 s50, s41, s43
	s_add_i32 s58, 0, 0x14000
	v_add_u32_e32 v124, s56, v201
	v_add_u32_e32 v168, s58, v201
	ds_read_b128 v[112:115], v124
	ds_read_b128 v[116:119], v124 offset:1024
	ds_read_b128 v[120:123], v124 offset:2048
	ds_read_b128 v[124:127], v124 offset:3072
	ds_read_b128 v[128:131], v168
	ds_read_b128 v[132:135], v168 offset:1024
	ds_read_b128 v[164:167], v168 offset:2048
	ds_read_b128 v[168:171], v168 offset:3072
	v_lshl_add_u64 v[178:179], s[48:49], 0, v[162:163]
	s_add_i32 m0, s21, 0xc000
	ds_read_b128 v[172:175], v203
	ds_read_b128 v[194:197], v203 offset:1024
	ds_read_b128 v[204:207], v203 offset:2048
	ds_read_b128 v[208:211], v203 offset:3072
	ds_read_b128 v[212:215], v203 offset:4096
	ds_read_b128 v[216:219], v203 offset:5120
	ds_read_b128 v[220:223], v203 offset:6144
	ds_read_b128 v[224:227], v203 offset:7168
	global_load_lds_dwordx4 v[178:179], off
	v_lshl_add_u64 v[178:179], s[48:49], 0, v[160:161]
	s_add_i32 m0, s21, 0xe000
	s_nop 0
	global_load_lds_dwordx4 v[178:179], off
	s_waitcnt vmcnt(8)
	s_waitcnt lgkmcnt(0)
	s_barrier
	v_mfma_f32_16x16x32_bf16 v[148:151], v[112:115], v[172:175], v[148:151]
	v_mfma_f32_16x16x32_bf16 v[144:147], v[120:123], v[172:175], v[144:147]
	v_mfma_f32_16x16x32_bf16 v[108:111], v[112:115], v[204:207], v[108:111]
	v_mfma_f32_16x16x32_bf16 v[104:107], v[120:123], v[204:207], v[104:107]
	v_mfma_f32_16x16x32_bf16 v[92:95], v[112:115], v[212:215], v[92:95]
	v_mfma_f32_16x16x32_bf16 v[88:91], v[120:123], v[212:215], v[88:91]
	v_mfma_f32_16x16x32_bf16 v[76:79], v[112:115], v[220:223], v[76:79]
	v_mfma_f32_16x16x32_bf16 v[72:75], v[120:123], v[220:223], v[72:75]
	v_mfma_f32_16x16x32_bf16 v[148:151], v[116:119], v[194:197], v[148:151]
	v_mfma_f32_16x16x32_bf16 v[144:147], v[124:127], v[194:197], v[144:147]
	v_mfma_f32_16x16x32_bf16 v[108:111], v[116:119], v[208:211], v[108:111]
	v_mfma_f32_16x16x32_bf16 v[104:107], v[124:127], v[208:211], v[104:107]
	v_mfma_f32_16x16x32_bf16 v[92:95], v[116:119], v[216:219], v[92:95]
	v_mfma_f32_16x16x32_bf16 v[88:91], v[124:127], v[216:219], v[88:91]
	v_mfma_f32_16x16x32_bf16 v[76:79], v[116:119], v[224:227], v[76:79]
	v_mfma_f32_16x16x32_bf16 v[72:75], v[124:127], v[224:227], v[72:75]
	v_mfma_f32_16x16x32_bf16 v[140:143], v[128:131], v[172:175], v[140:143]
	v_mfma_f32_16x16x32_bf16 v[136:139], v[164:167], v[172:175], v[136:139]
	v_mfma_f32_16x16x32_bf16 v[100:103], v[128:131], v[204:207], v[100:103]
	v_mfma_f32_16x16x32_bf16 v[96:99], v[164:167], v[204:207], v[96:99]
	v_mfma_f32_16x16x32_bf16 v[84:87], v[128:131], v[212:215], v[84:87]
	v_mfma_f32_16x16x32_bf16 v[80:83], v[164:167], v[212:215], v[80:83]
	v_mfma_f32_16x16x32_bf16 v[68:71], v[128:131], v[220:223], v[68:71]
	v_mfma_f32_16x16x32_bf16 v[64:67], v[164:167], v[220:223], v[64:67]
	v_mfma_f32_16x16x32_bf16 v[140:143], v[132:135], v[194:197], v[140:143]
	v_mfma_f32_16x16x32_bf16 v[136:139], v[168:171], v[194:197], v[136:139]
	v_mfma_f32_16x16x32_bf16 v[100:103], v[132:135], v[208:211], v[100:103]
	v_mfma_f32_16x16x32_bf16 v[96:99], v[168:171], v[208:211], v[96:99]
	v_mfma_f32_16x16x32_bf16 v[84:87], v[132:135], v[216:219], v[84:87]
	v_mfma_f32_16x16x32_bf16 v[80:83], v[168:171], v[216:219], v[80:83]
	v_mfma_f32_16x16x32_bf16 v[68:71], v[132:135], v[224:227], v[68:71]
	v_mfma_f32_16x16x32_bf16 v[64:67], v[168:171], v[224:227], v[64:67]
	s_barrier
	s_add_i32 s56, s56, s20
	v_lshl_add_u64 v[178:179], s[50:51], 0, v[156:157]
	s_mov_b32 m0, s56
	ds_read_b128 v[172:175], v203 offset:16384
	ds_read_b128 v[194:197], v203 offset:17408
	ds_read_b128 v[204:207], v203 offset:18432
	ds_read_b128 v[208:211], v203 offset:19456
	ds_read_b128 v[212:215], v203 offset:20480
	ds_read_b128 v[216:219], v203 offset:21504
	ds_read_b128 v[220:223], v203 offset:22528
	ds_read_b128 v[224:227], v203 offset:23552
	global_load_lds_dwordx4 v[178:179], off
	s_add_i32 m0, s56, 0x2000
	s_add_u32 s56, s50, 0x40000
	v_lshl_add_u64 v[198:199], s[50:51], 0, v[152:153]
	s_addc_u32 s57, s51, 0
	s_add_i32 s58, s58, s20
	global_load_lds_dwordx4 v[198:199], off
	v_lshl_add_u64 v[228:229], s[56:57], 0, v[156:157]
	s_mov_b32 m0, s58
	v_lshl_add_u64 v[230:231], s[52:53], 0, v[154:155]
	global_load_lds_dwordx4 v[228:229], off
	v_lshl_add_u64 v[228:229], s[56:57], 0, v[152:153]
	s_add_i32 m0, s58, 0x2000
	s_nop 0
	global_load_lds_dwordx4 v[228:229], off
	v_lshl_add_u64 v[228:229], s[52:53], 0, v[158:159]
	s_mov_b32 m0, s21
	s_nop 0
	global_load_lds_dwordx4 v[228:229], off
	s_mov_b32 m0, s22
	s_nop 0
	global_load_lds_dwordx4 v[230:231], off
	s_waitcnt vmcnt(8)
	s_waitcnt lgkmcnt(0)
	s_barrier
; #define PG8_STAGE(bufoff, gbase, voff) do { _Pragma("unroll") for (int _i = 0; _i < 2; ++_i) \
;         __builtin_amdgcn_global_load_lds((const unsigned*)((const char*)(gbase) + (voff)[_i]), (PG8_LAS unsigned*)(lds + (bufoff) + ldsw + _i * 8192), 16, 0, 0); } while (0)
; #define PG8_LDA(dst, b, h) do { _Pragma("unroll") for (int m = 0; m < 4; ++m) _Pragma("unroll") for (int k = 0; k < 2; ++k) dst[m][k] = *(const PG8_LAS bf16x8*)(lds + PG8_SA(b, h) + aoff + m * 2048 + k * 1024); } while (0)
; #define PG8_LDB(dst, b, h) do { _Pragma("unroll") for (int n = 0; n < 2; ++n) _Pragma("unroll") for (int k = 0; k < 2; ++k) dst[n][k] = *(const PG8_LAS bf16x8*)(lds + PG8_SB(b, h) + boff + n * 2048 + k * 1024); } while (0)
; #define PG8_MMA(ai, bj, At, Bt) do { __builtin_amdgcn_s_setprio(1); _Pragma("unroll") for (int m = 0; m < 4; ++m) _Pragma("unroll") for (int n = 0; n < 2; ++n) _Pragma("unroll") for (int k = 0; k < 2; ++k) \
;         acc[ai][bj][m][n] = __builtin_amdgcn_mfma_f32_16x16x32_bf16(Bt[n][k], At[m][k], acc[ai][bj][m][n], 0, 0, 0); __builtin_amdgcn_s_setprio(0); } while (0)
; #define PG8_WAIT_V(n) asm volatile("s_waitcnt vmcnt(" #n ")" ::: "memory")
; #define PG8_WAIT_L(n) asm volatile("s_waitcnt lgkmcnt(" #n ")" ::: "memory")
; #define PG8_BAR __builtin_amdgcn_s_barrier()
; #define PG8_SCHED __builtin_amdgcn_sched_barrier(0)
; template <class Epi, class Sched, bool ALIGN_EPI = false, bool SP2 = false>
; __device__ __forceinline__ void gemm_phase(PG8_LAS unsigned char* lds, const Gemm g, const Sched& S, const Epi& E) {
;     ...
;             PG8_WAIT_V(8); PG8_WAIT_L(0); PG8_BAR; PG8_MMA(1, 0, At, B0); PG8_MMA(1, 1, At, B1); PG8_BAR; PG8_SCHED;
;             PG8_LDB(B0, 1, 0); PG8_LDB(B1, 1, 1); PG8_SCHED; PG8_LDA(At, 1, 0); PG8_STAGE(PG8_SA(0, 1), a2 + hstep, voffA);
;             PG8_WAIT_V(8); PG8_WAIT_L(0); PG8_BAR; PG8_MMA(0, 0, At, B0); PG8_MMA(0, 1, At, B1); PG8_BAR; PG8_SCHED;
	v_mfma_f32_16x16x32_bf16 v[60:63], v[112:115], v[172:175], v[60:63]
	v_mfma_f32_16x16x32_bf16 v[56:59], v[120:123], v[172:175], v[56:59]
	v_mfma_f32_16x16x32_bf16 v[44:47], v[112:115], v[204:207], v[44:47]
	v_mfma_f32_16x16x32_bf16 v[40:43], v[120:123], v[204:207], v[40:43]
	v_mfma_f32_16x16x32_bf16 v[28:31], v[112:115], v[212:215], v[28:31]
	v_mfma_f32_16x16x32_bf16 v[24:27], v[120:123], v[212:215], v[24:27]
	v_mfma_f32_16x16x32_bf16 v[12:15], v[112:115], v[220:223], v[12:15]
	v_mfma_f32_16x16x32_bf16 v[8:11], v[120:123], v[220:223], v[8:11]
	v_mfma_f32_16x16x32_bf16 v[60:63], v[116:119], v[194:197], v[60:63]
	v_mfma_f32_16x16x32_bf16 v[56:59], v[124:127], v[194:197], v[56:59]
	v_mfma_f32_16x16x32_bf16 v[44:47], v[116:119], v[208:211], v[44:47]
	v_mfma_f32_16x16x32_bf16 v[40:43], v[124:127], v[208:211], v[40:43]
	v_mfma_f32_16x16x32_bf16 v[28:31], v[116:119], v[216:219], v[28:31]
	v_mfma_f32_16x16x32_bf16 v[24:27], v[124:127], v[216:219], v[24:27]
	v_mfma_f32_16x16x32_bf16 v[12:15], v[116:119], v[224:227], v[12:15]
	v_mfma_f32_16x16x32_bf16 v[8:11], v[124:127], v[224:227], v[8:11]
	v_mfma_f32_16x16x32_bf16 v[52:55], v[128:131], v[172:175], v[52:55]
	v_mfma_f32_16x16x32_bf16 v[48:51], v[164:167], v[172:175], v[48:51]
	v_mfma_f32_16x16x32_bf16 v[36:39], v[128:131], v[204:207], v[36:39]
	v_mfma_f32_16x16x32_bf16 v[32:35], v[164:167], v[204:207], v[32:35]
	v_mfma_f32_16x16x32_bf16 v[20:23], v[128:131], v[212:215], v[20:23]
	v_mfma_f32_16x16x32_bf16 v[16:19], v[164:167], v[212:215], v[16:19]
	v_mfma_f32_16x16x32_bf16 v[4:7], v[128:131], v[220:223], v[4:7]
	v_mfma_f32_16x16x32_bf16 v[0:3], v[164:167], v[220:223], v[0:3]
	v_mfma_f32_16x16x32_bf16 v[52:55], v[132:135], v[194:197], v[52:55]
	v_mfma_f32_16x16x32_bf16 v[48:51], v[168:171], v[194:197], v[48:51]
	v_mfma_f32_16x16x32_bf16 v[36:39], v[132:135], v[208:211], v[36:39]
	v_mfma_f32_16x16x32_bf16 v[32:35], v[168:171], v[208:211], v[32:35]
	v_mfma_f32_16x16x32_bf16 v[20:23], v[132:135], v[216:219], v[20:23]
	v_mfma_f32_16x16x32_bf16 v[16:19], v[168:171], v[216:219], v[16:19]
	v_mfma_f32_16x16x32_bf16 v[4:7], v[132:135], v[224:227], v[4:7]
	v_mfma_f32_16x16x32_bf16 v[0:3], v[168:171], v[224:227], v[0:3]
	s_barrier
	s_add_i32 s56, 0, 0x18000
	s_add_i32 s57, 0, 0x1c000
	v_add_u32_e32 v124, s56, v201
	v_add_u32_e32 v168, s57, v201
	ds_read_b128 v[112:115], v124
	ds_read_b128 v[116:119], v124 offset:1024
	ds_read_b128 v[120:123], v124 offset:2048
	ds_read_b128 v[124:127], v124 offset:3072
	ds_read_b128 v[128:131], v168
	ds_read_b128 v[132:135], v168 offset:1024
	ds_read_b128 v[164:167], v168 offset:2048
	ds_read_b128 v[168:171], v168 offset:3072
	s_add_u32 s52, s52, 0x40000
	s_addc_u32 s53, s53, 0
	s_mov_b32 m0, s23
	v_lshl_add_u64 v[232:233], s[52:53], 0, v[158:159]
	ds_read_b128 v[172:175], v203 offset:32768
	ds_read_b128 v[194:197], v203 offset:33792
	ds_read_b128 v[204:207], v203 offset:34816
	ds_read_b128 v[208:211], v203 offset:35840
	ds_read_b128 v[212:215], v203 offset:36864
	ds_read_b128 v[216:219], v203 offset:37888
	ds_read_b128 v[220:223], v203 offset:38912
	ds_read_b128 v[224:227], v203 offset:39936
	global_load_lds_dwordx4 v[232:233], off
	v_lshl_add_u64 v[232:233], s[52:53], 0, v[154:155]
	s_mov_b32 m0, s24
	s_nop 0
	global_load_lds_dwordx4 v[232:233], off
	s_waitcnt vmcnt(8)
	s_waitcnt lgkmcnt(0)
	s_barrier
	v_mfma_f32_16x16x32_bf16 v[148:151], v[112:115], v[172:175], v[148:151]
	v_mfma_f32_16x16x32_bf16 v[144:147], v[120:123], v[172:175], v[144:147]
	v_mfma_f32_16x16x32_bf16 v[108:111], v[112:115], v[204:207], v[108:111]
	v_mfma_f32_16x16x32_bf16 v[104:107], v[120:123], v[204:207], v[104:107]
	v_mfma_f32_16x16x32_bf16 v[92:95], v[112:115], v[212:215], v[92:95]
	v_mfma_f32_16x16x32_bf16 v[88:91], v[120:123], v[212:215], v[88:91]
	v_mfma_f32_16x16x32_bf16 v[76:79], v[112:115], v[220:223], v[76:79]
	v_mfma_f32_16x16x32_bf16 v[72:75], v[120:123], v[220:223], v[72:75]
	v_mfma_f32_16x16x32_bf16 v[148:151], v[116:119], v[194:197], v[148:151]
	v_mfma_f32_16x16x32_bf16 v[144:147], v[124:127], v[194:197], v[144:147]
	v_mfma_f32_16x16x32_bf16 v[108:111], v[116:119], v[208:211], v[108:111]
	v_mfma_f32_16x16x32_bf16 v[104:107], v[124:127], v[208:211], v[104:107]
	v_mfma_f32_16x16x32_bf16 v[92:95], v[116:119], v[216:219], v[92:95]
	v_mfma_f32_16x16x32_bf16 v[88:91], v[124:127], v[216:219], v[88:91]
	v_mfma_f32_16x16x32_bf16 v[76:79], v[116:119], v[224:227], v[76:79]
	v_mfma_f32_16x16x32_bf16 v[72:75], v[124:127], v[224:227], v[72:75]
	v_mfma_f32_16x16x32_bf16 v[140:143], v[128:131], v[172:175], v[140:143]
	v_mfma_f32_16x16x32_bf16 v[136:139], v[164:167], v[172:175], v[136:139]
	v_mfma_f32_16x16x32_bf16 v[100:103], v[128:131], v[204:207], v[100:103]
	v_mfma_f32_16x16x32_bf16 v[96:99], v[164:167], v[204:207], v[96:99]
	v_mfma_f32_16x16x32_bf16 v[84:87], v[128:131], v[212:215], v[84:87]
	v_mfma_f32_16x16x32_bf16 v[80:83], v[164:167], v[212:215], v[80:83]
	v_mfma_f32_16x16x32_bf16 v[68:71], v[128:131], v[220:223], v[68:71]
	v_mfma_f32_16x16x32_bf16 v[64:67], v[164:167], v[220:223], v[64:67]
	v_mfma_f32_16x16x32_bf16 v[140:143], v[132:135], v[194:197], v[140:143]
	v_mfma_f32_16x16x32_bf16 v[136:139], v[168:171], v[194:197], v[136:139]
	v_mfma_f32_16x16x32_bf16 v[100:103], v[132:135], v[208:211], v[100:103]
	v_mfma_f32_16x16x32_bf16 v[96:99], v[168:171], v[208:211], v[96:99]
	v_mfma_f32_16x16x32_bf16 v[84:87], v[132:135], v[216:219], v[84:87]
	v_mfma_f32_16x16x32_bf16 v[80:83], v[168:171], v[216:219], v[80:83]
	v_mfma_f32_16x16x32_bf16 v[68:71], v[132:135], v[224:227], v[68:71]
	v_mfma_f32_16x16x32_bf16 v[64:67], v[168:171], v[224:227], v[64:67]
	s_barrier
; #define PG8_STAGE(bufoff, gbase, voff) do { _Pragma("unroll") for (int _i = 0; _i < 2; ++_i) \
;         __builtin_amdgcn_global_load_lds((const unsigned*)((const char*)(gbase) + (voff)[_i]), (PG8_LAS unsigned*)(lds + (bufoff) + ldsw + _i * 8192), 16, 0, 0); } while (0)
; #define PG8_LDA(dst, b, h) do { _Pragma("unroll") for (int m = 0; m < 4; ++m) _Pragma("unroll") for (int k = 0; k < 2; ++k) dst[m][k] = *(const PG8_LAS bf16x8*)(lds + PG8_SA(b, h) + aoff + m * 2048 + k * 1024); } while (0)
; #define PG8_MMA(ai, bj, At, Bt) do { __builtin_amdgcn_s_setprio(1); _Pragma("unroll") for (int m = 0; m < 4; ++m) _Pragma("unroll") for (int n = 0; n < 2; ++n) _Pragma("unroll") for (int k = 0; k < 2; ++k) \
;         acc[ai][bj][m][n] = __builtin_amdgcn_mfma_f32_16x16x32_bf16(Bt[n][k], At[m][k], acc[ai][bj][m][n], 0, 0, 0); __builtin_amdgcn_s_setprio(0); } while (0)
; #define PG8_WAIT_V(n) asm volatile("s_waitcnt vmcnt(" #n ")" ::: "memory")
; #define PG8_WAIT_L(n) asm volatile("s_waitcnt lgkmcnt(" #n ")" ::: "memory")
; #define PG8_BAR __builtin_amdgcn_s_barrier()
; #define PG8_SCHED __builtin_amdgcn_sched_barrier(0)
; template <class Epi, class Sched, bool ALIGN_EPI = false, bool SP2 = false>
; __device__ __forceinline__ void gemm_phase(PG8_LAS unsigned char* lds, const Gemm g, const Sched& S, const Epi& E) {
;     ...
;             PG8_LDA(At, 1, 1); PG8_STAGE(PG8_SB(1, 0), b3, voffB); PG8_STAGE(PG8_SB(1, 1), b3 + hstep, voffB); PG8_STAGE(PG8_SA(1, 0), a3, voffA);
;             PG8_WAIT_V(8); PG8_WAIT_L(0); PG8_BAR; PG8_MMA(1, 0, At, B0); PG8_MMA(1, 1, At, B1); PG8_BAR; PG8_SCHED;
;     ...
;         if constexpr (ALIGN_EPI) { if (wr == 0) PG8_BAR; }
	s_add_i32 s52, s56, s20
	v_lshl_add_u64 v[178:179], v[178:179], 0, s[36:37]
	s_mov_b32 m0, s52
	ds_read_b128 v[172:175], v203 offset:49152
	ds_read_b128 v[194:197], v203 offset:50176
	ds_read_b128 v[204:207], v203 offset:51200
	ds_read_b128 v[208:211], v203 offset:52224
	ds_read_b128 v[212:215], v203 offset:53248
	ds_read_b128 v[216:219], v203 offset:54272
	ds_read_b128 v[220:223], v203 offset:55296
	ds_read_b128 v[224:227], v203 offset:56320
	global_load_lds_dwordx4 v[178:179], off
	s_add_i32 m0, s52, 0x2000
	s_add_u32 s50, s50, 0x40080
	v_lshl_add_u64 v[178:179], v[198:199], 0, s[36:37]
	s_addc_u32 s51, s51, 0
	s_add_i32 s52, s57, s20
	global_load_lds_dwordx4 v[178:179], off
	v_lshl_add_u64 v[178:179], s[50:51], 0, v[156:157]
	s_mov_b32 m0, s52
	s_nop 0
	global_load_lds_dwordx4 v[178:179], off
	v_lshl_add_u64 v[178:179], s[50:51], 0, v[152:153]
	s_add_i32 m0, s52, 0x2000
	s_nop 0
	global_load_lds_dwordx4 v[178:179], off
	v_lshl_add_u64 v[178:179], v[228:229], 0, s[36:37]
	s_mov_b32 m0, s28
	s_nop 0
	global_load_lds_dwordx4 v[178:179], off
	v_lshl_add_u64 v[178:179], v[230:231], 0, s[36:37]
	s_mov_b32 m0, s29
	s_nop 0
	global_load_lds_dwordx4 v[178:179], off
	s_waitcnt vmcnt(8)
	s_waitcnt lgkmcnt(0)
	s_barrier
	v_mfma_f32_16x16x32_bf16 v[60:63], v[112:115], v[172:175], v[60:63]
	v_mfma_f32_16x16x32_bf16 v[56:59], v[120:123], v[172:175], v[56:59]
	v_mfma_f32_16x16x32_bf16 v[44:47], v[112:115], v[204:207], v[44:47]
	v_mfma_f32_16x16x32_bf16 v[40:43], v[120:123], v[204:207], v[40:43]
	v_mfma_f32_16x16x32_bf16 v[28:31], v[112:115], v[212:215], v[28:31]
	v_mfma_f32_16x16x32_bf16 v[24:27], v[120:123], v[212:215], v[24:27]
	v_mfma_f32_16x16x32_bf16 v[12:15], v[112:115], v[220:223], v[12:15]
	v_mfma_f32_16x16x32_bf16 v[8:11], v[120:123], v[220:223], v[8:11]
	v_mfma_f32_16x16x32_bf16 v[60:63], v[116:119], v[194:197], v[60:63]
	v_mfma_f32_16x16x32_bf16 v[56:59], v[124:127], v[194:197], v[56:59]
	v_mfma_f32_16x16x32_bf16 v[44:47], v[116:119], v[208:211], v[44:47]
	v_mfma_f32_16x16x32_bf16 v[40:43], v[124:127], v[208:211], v[40:43]
	v_mfma_f32_16x16x32_bf16 v[28:31], v[116:119], v[216:219], v[28:31]
	v_mfma_f32_16x16x32_bf16 v[24:27], v[124:127], v[216:219], v[24:27]
	v_mfma_f32_16x16x32_bf16 v[12:15], v[116:119], v[224:227], v[12:15]
	v_mfma_f32_16x16x32_bf16 v[8:11], v[124:127], v[224:227], v[8:11]
	v_mfma_f32_16x16x32_bf16 v[52:55], v[128:131], v[172:175], v[52:55]
	v_mfma_f32_16x16x32_bf16 v[48:51], v[164:167], v[172:175], v[48:51]
	v_mfma_f32_16x16x32_bf16 v[36:39], v[128:131], v[204:207], v[36:39]
	v_mfma_f32_16x16x32_bf16 v[32:35], v[164:167], v[204:207], v[32:35]
	v_mfma_f32_16x16x32_bf16 v[20:23], v[128:131], v[212:215], v[20:23]
	v_mfma_f32_16x16x32_bf16 v[16:19], v[164:167], v[212:215], v[16:19]
	v_mfma_f32_16x16x32_bf16 v[4:7], v[128:131], v[220:223], v[4:7]
	v_mfma_f32_16x16x32_bf16 v[0:3], v[164:167], v[220:223], v[0:3]
	v_mfma_f32_16x16x32_bf16 v[52:55], v[132:135], v[194:197], v[52:55]
	v_mfma_f32_16x16x32_bf16 v[48:51], v[168:171], v[194:197], v[48:51]
	v_mfma_f32_16x16x32_bf16 v[36:39], v[132:135], v[208:211], v[36:39]
	v_mfma_f32_16x16x32_bf16 v[32:35], v[168:171], v[208:211], v[32:35]
	v_mfma_f32_16x16x32_bf16 v[20:23], v[132:135], v[216:219], v[20:23]
	v_mfma_f32_16x16x32_bf16 v[16:19], v[168:171], v[216:219], v[16:19]
	v_mfma_f32_16x16x32_bf16 v[4:7], v[132:135], v[224:227], v[4:7]
	v_mfma_f32_16x16x32_bf16 v[0:3], v[168:171], v[224:227], v[0:3]
	s_barrier
	s_add_i32 s55, s55, 2
	s_add_u32 s43, s43, 0x100
	s_addc_u32 s54, s54, 0
	s_add_u32 s48, s48, 0x100
	s_addc_u32 s49, s49, 0
	s_cmp_gt_u32 s55, 13
	s_cbranch_scc0 .LBB0_558
	s_and_b64 vcc, exec, s[26:27]
	s_cbranch_vccz .LBB0_561
	s_barrier

; #define PG8_STAGE(bufoff, gbase, voff) do { _Pragma("unroll") for (int _i = 0; _i < 2; ++_i) \
;         __builtin_amdgcn_global_load_lds((const unsigned*)((const char*)(gbase) + (voff)[_i]), (PG8_LAS unsigned*)(lds + (bufoff) + ldsw + _i * 8192), 16, 0, 0); } while (0)
; #define PG8_LDA(dst, b, h) do { _Pragma("unroll") for (int m = 0; m < 4; ++m) _Pragma("unroll") for (int k = 0; k < 2; ++k) dst[m][k] = *(const PG8_LAS bf16x8*)(lds + PG8_SA(b, h) + aoff + m * 2048 + k * 1024); } while (0)
; #define PG8_LDB(dst, b, h) do { _Pragma("unroll") for (int n = 0; n < 2; ++n) _Pragma("unroll") for (int k = 0; k < 2; ++k) dst[n][k] = *(const PG8_LAS bf16x8*)(lds + PG8_SB(b, h) + boff + n * 2048 + k * 1024); } while (0)
; #define PG8_MMA(ai, bj, At, Bt) do { __builtin_amdgcn_s_setprio(1); _Pragma("unroll") for (int m = 0; m < 4; ++m) _Pragma("unroll") for (int n = 0; n < 2; ++n) _Pragma("unroll") for (int k = 0; k < 2; ++k) \
;         acc[ai][bj][m][n] = __builtin_amdgcn_mfma_f32_16x16x32_bf16(Bt[n][k], At[m][k], acc[ai][bj][m][n], 0, 0, 0); __builtin_amdgcn_s_setprio(0); } while (0)
; #define PG8_WAIT_V(n) asm volatile("s_waitcnt vmcnt(" #n ")" ::: "memory")
; #define PG8_WAIT_L(n) asm volatile("s_waitcnt lgkmcnt(" #n ")" ::: "memory")
; template <class Epi, class Sched, bool ALIGN_EPI = false, bool SP2 = false>
; __device__ __forceinline__ void gemm_phase(PG8_LAS unsigned char* lds, const Gemm g, const Sched& S, const Epi& E) {
;     ...
;             const bool last = (t == nt - 2);
;             const char* a1 = cA + (size_t)(t + 1) * kstep;
;             const char* a2 = last ? nA : cA + (size_t)(t + 2) * kstep; const char* b2 = last ? nB : cB + (size_t)(t + 2) * kstep;
;             const char* a3 = a2 + kstep; const char* b3 = b2 + kstep;
;             if (last && has_next) S.a_ready(nxt);
;             if constexpr (SP2) {
;             PG8_LDB(B0, 0, 0); PG8_LDB(B1, 0, 1); PG8_SCHED; PG8_LDA(At, 0, 0); PG8_STAGE(PG8_SA(1, 1), a1 + hstep, voffA);
;             PG8_WAIT_V(8); PG8_WAIT_L(0); PG8_BAR; PG8_MMA(0, 0, At, B0); PG8_MMA(0, 1, At, B1); PG8_BAR; PG8_SCHED;
;             PG8_LDA(At, 0, 1); PG8_STAGE(PG8_SB(0, 0), b2, voffB); PG8_STAGE(PG8_SB(0, 1), b2 + hstep, voffB); PG8_STAGE(PG8_SA(0, 0), a2, voffA);
;             PG8_WAIT_V(8); PG8_WAIT_L(0); PG8_BAR; PG8_MMA(1, 0, At, B0); PG8_MMA(1, 1, At, B1); PG8_BAR; PG8_SCHED;
.LBB0_659:
	s_add_u32 s48, s46, 0xfffc0080
	s_addc_u32 s49, s47, -1
	s_add_i32 s54, 0, 0x10000
	s_cmp_eq_u32 s53, 12
	s_cselect_b32 s51, s33, s49
	s_cselect_b32 s50, s34, s48
	v_add_u32_e32 v141, s54, v148
	s_cselect_b32 s49, s27, s52
	s_cselect_b32 s48, s35, s41
	s_add_i32 s56, 0, 0x14000
	ds_read_b128 v[142:145], v141
	ds_read_b128 v[152:155], v141 offset:1024
	ds_read_b128 v[156:159], v141 offset:2048
	ds_read_b128 v[160:163], v141 offset:3072
	v_add_u32_e32 v141, s56, v148
	ds_read_b128 v[164:167], v141
	ds_read_b128 v[168:171], v141 offset:1024
	ds_read_b128 v[172:175], v141 offset:2048
	ds_read_b128 v[194:197], v141 offset:3072
	v_lshl_add_u64 v[178:179], s[46:47], 0, v[138:139]
	s_add_i32 m0, s21, 0xc000
	ds_read_b128 v[198:201], v151
	ds_read_b128 v[202:205], v151 offset:1024
	ds_read_b128 v[206:209], v151 offset:2048
	ds_read_b128 v[210:213], v151 offset:3072
	ds_read_b128 v[214:217], v151 offset:4096
	ds_read_b128 v[218:221], v151 offset:5120
	ds_read_b128 v[222:225], v151 offset:6144
	ds_read_b128 v[226:229], v151 offset:7168
	global_load_lds_dwordx4 v[178:179], off
	v_lshl_add_u64 v[178:179], s[46:47], 0, v[136:137]
	s_add_i32 m0, s21, 0xe000
	s_nop 0
	global_load_lds_dwordx4 v[178:179], off
	s_waitcnt vmcnt(8)
	s_waitcnt lgkmcnt(0)
	s_barrier
	v_mfma_f32_16x16x32_bf16 v[124:127], v[142:145], v[198:201], v[124:127]
	v_mfma_f32_16x16x32_bf16 v[120:123], v[156:159], v[198:201], v[120:123]
	v_mfma_f32_16x16x32_bf16 v[108:111], v[142:145], v[206:209], v[108:111]
	v_mfma_f32_16x16x32_bf16 v[104:107], v[156:159], v[206:209], v[104:107]
	v_mfma_f32_16x16x32_bf16 v[92:95], v[142:145], v[214:217], v[92:95]
	v_mfma_f32_16x16x32_bf16 v[88:91], v[156:159], v[214:217], v[88:91]
	v_mfma_f32_16x16x32_bf16 v[76:79], v[142:145], v[222:225], v[76:79]
	v_mfma_f32_16x16x32_bf16 v[72:75], v[156:159], v[222:225], v[72:75]
	v_mfma_f32_16x16x32_bf16 v[124:127], v[152:155], v[202:205], v[124:127]
	v_mfma_f32_16x16x32_bf16 v[120:123], v[160:163], v[202:205], v[120:123]
	v_mfma_f32_16x16x32_bf16 v[108:111], v[152:155], v[210:213], v[108:111]
	v_mfma_f32_16x16x32_bf16 v[104:107], v[160:163], v[210:213], v[104:107]
	v_mfma_f32_16x16x32_bf16 v[92:95], v[152:155], v[218:221], v[92:95]
	v_mfma_f32_16x16x32_bf16 v[88:91], v[160:163], v[218:221], v[88:91]
	v_mfma_f32_16x16x32_bf16 v[76:79], v[152:155], v[226:229], v[76:79]
	v_mfma_f32_16x16x32_bf16 v[72:75], v[160:163], v[226:229], v[72:75]
	v_mfma_f32_16x16x32_bf16 v[116:119], v[164:167], v[198:201], v[116:119]
	v_mfma_f32_16x16x32_bf16 v[112:115], v[172:175], v[198:201], v[112:115]
	v_mfma_f32_16x16x32_bf16 v[100:103], v[164:167], v[206:209], v[100:103]
	v_mfma_f32_16x16x32_bf16 v[96:99], v[172:175], v[206:209], v[96:99]
	v_mfma_f32_16x16x32_bf16 v[84:87], v[164:167], v[214:217], v[84:87]
	v_mfma_f32_16x16x32_bf16 v[80:83], v[172:175], v[214:217], v[80:83]
	v_mfma_f32_16x16x32_bf16 v[68:71], v[164:167], v[222:225], v[68:71]
	v_mfma_f32_16x16x32_bf16 v[64:67], v[172:175], v[222:225], v[64:67]
	v_mfma_f32_16x16x32_bf16 v[116:119], v[168:171], v[202:205], v[116:119]
	v_mfma_f32_16x16x32_bf16 v[112:115], v[194:197], v[202:205], v[112:115]
	v_mfma_f32_16x16x32_bf16 v[100:103], v[168:171], v[210:213], v[100:103]
	v_mfma_f32_16x16x32_bf16 v[96:99], v[194:197], v[210:213], v[96:99]
	v_mfma_f32_16x16x32_bf16 v[84:87], v[168:171], v[218:221], v[84:87]
	v_mfma_f32_16x16x32_bf16 v[80:83], v[194:197], v[218:221], v[80:83]
	v_mfma_f32_16x16x32_bf16 v[68:71], v[168:171], v[226:229], v[68:71]
	v_mfma_f32_16x16x32_bf16 v[64:67], v[194:197], v[226:229], v[64:67]
	s_barrier
	s_add_i32 s54, s54, s20
	v_lshl_add_u64 v[178:179], s[48:49], 0, v[132:133]
	s_mov_b32 m0, s54
	ds_read_b128 v[198:201], v151 offset:16384
	ds_read_b128 v[202:205], v151 offset:17408
	ds_read_b128 v[206:209], v151 offset:18432
	ds_read_b128 v[210:213], v151 offset:19456
	ds_read_b128 v[214:217], v151 offset:20480
	ds_read_b128 v[218:221], v151 offset:21504
	ds_read_b128 v[222:225], v151 offset:22528
	ds_read_b128 v[226:229], v151 offset:23552
	global_load_lds_dwordx4 v[178:179], off
	s_add_i32 m0, s54, 0x2000
	s_add_u32 s54, s48, 0x40000
	v_lshl_add_u64 v[230:231], s[48:49], 0, v[128:129]
	s_addc_u32 s55, s49, 0
	s_add_i32 s56, s56, s20
	global_load_lds_dwordx4 v[230:231], off
	v_lshl_add_u64 v[232:233], s[54:55], 0, v[132:133]
	s_mov_b32 m0, s56
	v_lshl_add_u64 v[234:235], s[50:51], 0, v[130:131]
	global_load_lds_dwordx4 v[232:233], off
	v_lshl_add_u64 v[232:233], s[54:55], 0, v[128:129]
	s_add_i32 m0, s56, 0x2000
	s_nop 0
	global_load_lds_dwordx4 v[232:233], off
	v_lshl_add_u64 v[232:233], s[50:51], 0, v[134:135]
	s_mov_b32 m0, s21
	s_nop 0
	global_load_lds_dwordx4 v[232:233], off
	s_mov_b32 m0, s22
	s_nop 0
	global_load_lds_dwordx4 v[234:235], off
	s_waitcnt vmcnt(8)
	s_waitcnt lgkmcnt(0)
	s_barrier
; #define PG8_STAGE(bufoff, gbase, voff) do { _Pragma("unroll") for (int _i = 0; _i < 2; ++_i) \
;         __builtin_amdgcn_global_load_lds((const unsigned*)((const char*)(gbase) + (voff)[_i]), (PG8_LAS unsigned*)(lds + (bufoff) + ldsw + _i * 8192), 16, 0, 0); } while (0)
; #define PG8_LDA(dst, b, h) do { _Pragma("unroll") for (int m = 0; m < 4; ++m) _Pragma("unroll") for (int k = 0; k < 2; ++k) dst[m][k] = *(const PG8_LAS bf16x8*)(lds + PG8_SA(b, h) + aoff + m * 2048 + k * 1024); } while (0)
; #define PG8_LDB(dst, b, h) do { _Pragma("unroll") for (int n = 0; n < 2; ++n) _Pragma("unroll") for (int k = 0; k < 2; ++k) dst[n][k] = *(const PG8_LAS bf16x8*)(lds + PG8_SB(b, h) + boff + n * 2048 + k * 1024); } while (0)
; #define PG8_MMA(ai, bj, At, Bt) do { __builtin_amdgcn_s_setprio(1); _Pragma("unroll") for (int m = 0; m < 4; ++m) _Pragma("unroll") for (int n = 0; n < 2; ++n) _Pragma("unroll") for (int k = 0; k < 2; ++k) \
;         acc[ai][bj][m][n] = __builtin_amdgcn_mfma_f32_16x16x32_bf16(Bt[n][k], At[m][k], acc[ai][bj][m][n], 0, 0, 0); __builtin_amdgcn_s_setprio(0); } while (0)
; #define PG8_WAIT_V(n) asm volatile("s_waitcnt vmcnt(" #n ")" ::: "memory")
; #define PG8_WAIT_L(n) asm volatile("s_waitcnt lgkmcnt(" #n ")" ::: "memory")
; #define PG8_BAR __builtin_amdgcn_s_barrier()
; #define PG8_SCHED __builtin_amdgcn_sched_barrier(0)
; template <class Epi, class Sched, bool ALIGN_EPI = false, bool SP2 = false>
; __device__ __forceinline__ void gemm_phase(PG8_LAS unsigned char* lds, const Gemm g, const Sched& S, const Epi& E) {
;     ...
;             PG8_WAIT_V(8); PG8_WAIT_L(0); PG8_BAR; PG8_MMA(1, 0, At, B0); PG8_MMA(1, 1, At, B1); PG8_BAR; PG8_SCHED;
;             PG8_LDB(B0, 1, 0); PG8_LDB(B1, 1, 1); PG8_SCHED; PG8_LDA(At, 1, 0); PG8_STAGE(PG8_SA(0, 1), a2 + hstep, voffA);
;             PG8_WAIT_V(8); PG8_WAIT_L(0); PG8_BAR; PG8_MMA(0, 0, At, B0); PG8_MMA(0, 1, At, B1); PG8_BAR; PG8_SCHED;
	v_mfma_f32_16x16x32_bf16 v[60:63], v[142:145], v[198:201], v[60:63]
	v_mfma_f32_16x16x32_bf16 v[56:59], v[156:159], v[198:201], v[56:59]
	v_mfma_f32_16x16x32_bf16 v[44:47], v[142:145], v[206:209], v[44:47]
	v_mfma_f32_16x16x32_bf16 v[40:43], v[156:159], v[206:209], v[40:43]
	v_mfma_f32_16x16x32_bf16 v[28:31], v[142:145], v[214:217], v[28:31]
	v_mfma_f32_16x16x32_bf16 v[24:27], v[156:159], v[214:217], v[24:27]
	v_mfma_f32_16x16x32_bf16 v[12:15], v[142:145], v[222:225], v[12:15]
	v_mfma_f32_16x16x32_bf16 v[8:11], v[156:159], v[222:225], v[8:11]
	v_mfma_f32_16x16x32_bf16 v[60:63], v[152:155], v[202:205], v[60:63]
	v_mfma_f32_16x16x32_bf16 v[56:59], v[160:163], v[202:205], v[56:59]
	v_mfma_f32_16x16x32_bf16 v[44:47], v[152:155], v[210:213], v[44:47]
	v_mfma_f32_16x16x32_bf16 v[40:43], v[160:163], v[210:213], v[40:43]
	v_mfma_f32_16x16x32_bf16 v[28:31], v[152:155], v[218:221], v[28:31]
	v_mfma_f32_16x16x32_bf16 v[24:27], v[160:163], v[218:221], v[24:27]
	v_mfma_f32_16x16x32_bf16 v[12:15], v[152:155], v[226:229], v[12:15]
	v_mfma_f32_16x16x32_bf16 v[8:11], v[160:163], v[226:229], v[8:11]
	v_mfma_f32_16x16x32_bf16 v[52:55], v[164:167], v[198:201], v[52:55]
	v_mfma_f32_16x16x32_bf16 v[48:51], v[172:175], v[198:201], v[48:51]
	v_mfma_f32_16x16x32_bf16 v[36:39], v[164:167], v[206:209], v[36:39]
	v_mfma_f32_16x16x32_bf16 v[32:35], v[172:175], v[206:209], v[32:35]
	v_mfma_f32_16x16x32_bf16 v[20:23], v[164:167], v[214:217], v[20:23]
	v_mfma_f32_16x16x32_bf16 v[16:19], v[172:175], v[214:217], v[16:19]
	v_mfma_f32_16x16x32_bf16 v[4:7], v[164:167], v[222:225], v[4:7]
	v_mfma_f32_16x16x32_bf16 v[0:3], v[172:175], v[222:225], v[0:3]
	v_mfma_f32_16x16x32_bf16 v[52:55], v[168:171], v[202:205], v[52:55]
	v_mfma_f32_16x16x32_bf16 v[48:51], v[194:197], v[202:205], v[48:51]
	v_mfma_f32_16x16x32_bf16 v[36:39], v[168:171], v[210:213], v[36:39]
	v_mfma_f32_16x16x32_bf16 v[32:35], v[194:197], v[210:213], v[32:35]
	v_mfma_f32_16x16x32_bf16 v[20:23], v[168:171], v[218:221], v[20:23]
	v_mfma_f32_16x16x32_bf16 v[16:19], v[194:197], v[218:221], v[16:19]
	v_mfma_f32_16x16x32_bf16 v[4:7], v[168:171], v[226:229], v[4:7]
	v_mfma_f32_16x16x32_bf16 v[0:3], v[194:197], v[226:229], v[0:3]
	s_barrier
	s_add_i32 s54, 0, 0x18000
	v_add_u32_e32 v141, s54, v148
	s_add_i32 s55, 0, 0x1c000
	ds_read_b128 v[142:145], v141
	ds_read_b128 v[152:155], v141 offset:1024
	ds_read_b128 v[156:159], v141 offset:2048
	ds_read_b128 v[160:163], v141 offset:3072
	v_add_u32_e32 v141, s55, v148
	ds_read_b128 v[164:167], v141
	ds_read_b128 v[168:171], v141 offset:1024
	ds_read_b128 v[172:175], v141 offset:2048
	ds_read_b128 v[194:197], v141 offset:3072
	s_add_u32 s50, s50, 0x40000
	s_addc_u32 s51, s51, 0
	s_mov_b32 m0, s23
	v_lshl_add_u64 v[236:237], s[50:51], 0, v[134:135]
	ds_read_b128 v[198:201], v151 offset:32768
	ds_read_b128 v[202:205], v151 offset:33792
	ds_read_b128 v[206:209], v151 offset:34816
	ds_read_b128 v[210:213], v151 offset:35840
	ds_read_b128 v[214:217], v151 offset:36864
	ds_read_b128 v[218:221], v151 offset:37888
	ds_read_b128 v[222:225], v151 offset:38912
	ds_read_b128 v[226:229], v151 offset:39936
	global_load_lds_dwordx4 v[236:237], off
	v_lshl_add_u64 v[236:237], s[50:51], 0, v[130:131]
	s_mov_b32 m0, s24
	s_nop 0
	global_load_lds_dwordx4 v[236:237], off
	s_waitcnt vmcnt(8)
	s_waitcnt lgkmcnt(0)
	s_barrier
	v_mfma_f32_16x16x32_bf16 v[124:127], v[142:145], v[198:201], v[124:127]
	v_mfma_f32_16x16x32_bf16 v[120:123], v[156:159], v[198:201], v[120:123]
	v_mfma_f32_16x16x32_bf16 v[108:111], v[142:145], v[206:209], v[108:111]
	v_mfma_f32_16x16x32_bf16 v[104:107], v[156:159], v[206:209], v[104:107]
	v_mfma_f32_16x16x32_bf16 v[92:95], v[142:145], v[214:217], v[92:95]
	v_mfma_f32_16x16x32_bf16 v[88:91], v[156:159], v[214:217], v[88:91]
	v_mfma_f32_16x16x32_bf16 v[76:79], v[142:145], v[222:225], v[76:79]
	v_mfma_f32_16x16x32_bf16 v[72:75], v[156:159], v[222:225], v[72:75]
	v_mfma_f32_16x16x32_bf16 v[124:127], v[152:155], v[202:205], v[124:127]
	v_mfma_f32_16x16x32_bf16 v[120:123], v[160:163], v[202:205], v[120:123]
	v_mfma_f32_16x16x32_bf16 v[108:111], v[152:155], v[210:213], v[108:111]
	v_mfma_f32_16x16x32_bf16 v[104:107], v[160:163], v[210:213], v[104:107]
	v_mfma_f32_16x16x32_bf16 v[92:95], v[152:155], v[218:221], v[92:95]
	v_mfma_f32_16x16x32_bf16 v[88:91], v[160:163], v[218:221], v[88:91]
	v_mfma_f32_16x16x32_bf16 v[76:79], v[152:155], v[226:229], v[76:79]
	v_mfma_f32_16x16x32_bf16 v[72:75], v[160:163], v[226:229], v[72:75]
	v_mfma_f32_16x16x32_bf16 v[116:119], v[164:167], v[198:201], v[116:119]
	v_mfma_f32_16x16x32_bf16 v[112:115], v[172:175], v[198:201], v[112:115]
	v_mfma_f32_16x16x32_bf16 v[100:103], v[164:167], v[206:209], v[100:103]
	v_mfma_f32_16x16x32_bf16 v[96:99], v[172:175], v[206:209], v[96:99]
	v_mfma_f32_16x16x32_bf16 v[84:87], v[164:167], v[214:217], v[84:87]
	v_mfma_f32_16x16x32_bf16 v[80:83], v[172:175], v[214:217], v[80:83]
	v_mfma_f32_16x16x32_bf16 v[68:71], v[164:167], v[222:225], v[68:71]
	v_mfma_f32_16x16x32_bf16 v[64:67], v[172:175], v[222:225], v[64:67]
	v_mfma_f32_16x16x32_bf16 v[116:119], v[168:171], v[202:205], v[116:119]
	v_mfma_f32_16x16x32_bf16 v[112:115], v[194:197], v[202:205], v[112:115]
	v_mfma_f32_16x16x32_bf16 v[100:103], v[168:171], v[210:213], v[100:103]
	v_mfma_f32_16x16x32_bf16 v[96:99], v[194:197], v[210:213], v[96:99]
	v_mfma_f32_16x16x32_bf16 v[84:87], v[168:171], v[218:221], v[84:87]
	v_mfma_f32_16x16x32_bf16 v[80:83], v[194:197], v[218:221], v[80:83]
	v_mfma_f32_16x16x32_bf16 v[68:71], v[168:171], v[226:229], v[68:71]
	v_mfma_f32_16x16x32_bf16 v[64:67], v[194:197], v[226:229], v[64:67]
	s_barrier
; #define PG8_STAGE(bufoff, gbase, voff) do { _Pragma("unroll") for (int _i = 0; _i < 2; ++_i) \
;         __builtin_amdgcn_global_load_lds((const unsigned*)((const char*)(gbase) + (voff)[_i]), (PG8_LAS unsigned*)(lds + (bufoff) + ldsw + _i * 8192), 16, 0, 0); } while (0)
; #define PG8_LDA(dst, b, h) do { _Pragma("unroll") for (int m = 0; m < 4; ++m) _Pragma("unroll") for (int k = 0; k < 2; ++k) dst[m][k] = *(const PG8_LAS bf16x8*)(lds + PG8_SA(b, h) + aoff + m * 2048 + k * 1024); } while (0)
; #define PG8_MMA(ai, bj, At, Bt) do { __builtin_amdgcn_s_setprio(1); _Pragma("unroll") for (int m = 0; m < 4; ++m) _Pragma("unroll") for (int n = 0; n < 2; ++n) _Pragma("unroll") for (int k = 0; k < 2; ++k) \
;         acc[ai][bj][m][n] = __builtin_amdgcn_mfma_f32_16x16x32_bf16(Bt[n][k], At[m][k], acc[ai][bj][m][n], 0, 0, 0); __builtin_amdgcn_s_setprio(0); } while (0)
; #define PG8_WAIT_V(n) asm volatile("s_waitcnt vmcnt(" #n ")" ::: "memory")
; #define PG8_WAIT_L(n) asm volatile("s_waitcnt lgkmcnt(" #n ")" ::: "memory")
; #define PG8_BAR __builtin_amdgcn_s_barrier()
; #define PG8_SCHED __builtin_amdgcn_sched_barrier(0)
; template <class Epi, class Sched, bool ALIGN_EPI = false, bool SP2 = false>
; __device__ __forceinline__ void gemm_phase(PG8_LAS unsigned char* lds, const Gemm g, const Sched& S, const Epi& E) {
;     ...
;             PG8_LDA(At, 1, 1); PG8_STAGE(PG8_SB(1, 0), b3, voffB); PG8_STAGE(PG8_SB(1, 1), b3 + hstep, voffB); PG8_STAGE(PG8_SA(1, 0), a3, voffA);
;             PG8_WAIT_V(8); PG8_WAIT_L(0); PG8_BAR; PG8_MMA(1, 0, At, B0); PG8_MMA(1, 1, At, B1); PG8_BAR; PG8_SCHED;
;     ...
;         if constexpr (ALIGN_EPI) { if (wr == 0) PG8_BAR; }
	s_add_i32 s50, s54, s20
	v_lshl_add_u64 v[178:179], v[178:179], 0, s[36:37]
	s_mov_b32 m0, s50
	ds_read_b128 v[198:201], v151 offset:49152
	ds_read_b128 v[202:205], v151 offset:50176
	ds_read_b128 v[206:209], v151 offset:51200
	ds_read_b128 v[210:213], v151 offset:52224
	ds_read_b128 v[214:217], v151 offset:53248
	ds_read_b128 v[218:221], v151 offset:54272
	ds_read_b128 v[222:225], v151 offset:55296
	ds_read_b128 v[226:229], v151 offset:56320
	global_load_lds_dwordx4 v[178:179], off
	s_add_i32 m0, s50, 0x2000
	s_add_u32 s48, s48, 0x40080
	v_lshl_add_u64 v[178:179], v[230:231], 0, s[36:37]
	s_addc_u32 s49, s49, 0
	s_add_i32 s50, s55, s20
	global_load_lds_dwordx4 v[178:179], off
	v_lshl_add_u64 v[178:179], s[48:49], 0, v[132:133]
	s_mov_b32 m0, s50
	s_nop 0
	global_load_lds_dwordx4 v[178:179], off
	v_lshl_add_u64 v[178:179], s[48:49], 0, v[128:129]
	s_add_i32 m0, s50, 0x2000
	s_nop 0
	global_load_lds_dwordx4 v[178:179], off
	v_lshl_add_u64 v[178:179], v[232:233], 0, s[36:37]
	s_mov_b32 m0, s25
	s_nop 0
	global_load_lds_dwordx4 v[178:179], off
	v_lshl_add_u64 v[178:179], v[234:235], 0, s[36:37]
	s_mov_b32 m0, s28
	s_nop 0
	global_load_lds_dwordx4 v[178:179], off
	s_waitcnt vmcnt(8)
	s_waitcnt lgkmcnt(0)
	s_barrier
	v_mfma_f32_16x16x32_bf16 v[60:63], v[142:145], v[198:201], v[60:63]
	v_mfma_f32_16x16x32_bf16 v[56:59], v[156:159], v[198:201], v[56:59]
	v_mfma_f32_16x16x32_bf16 v[44:47], v[142:145], v[206:209], v[44:47]
	v_mfma_f32_16x16x32_bf16 v[40:43], v[156:159], v[206:209], v[40:43]
	v_mfma_f32_16x16x32_bf16 v[28:31], v[142:145], v[214:217], v[28:31]
	v_mfma_f32_16x16x32_bf16 v[24:27], v[156:159], v[214:217], v[24:27]
	v_mfma_f32_16x16x32_bf16 v[12:15], v[142:145], v[222:225], v[12:15]
	v_mfma_f32_16x16x32_bf16 v[8:11], v[156:159], v[222:225], v[8:11]
	v_mfma_f32_16x16x32_bf16 v[60:63], v[152:155], v[202:205], v[60:63]
	v_mfma_f32_16x16x32_bf16 v[56:59], v[160:163], v[202:205], v[56:59]
	v_mfma_f32_16x16x32_bf16 v[44:47], v[152:155], v[210:213], v[44:47]
	v_mfma_f32_16x16x32_bf16 v[40:43], v[160:163], v[210:213], v[40:43]
	v_mfma_f32_16x16x32_bf16 v[28:31], v[152:155], v[218:221], v[28:31]
	v_mfma_f32_16x16x32_bf16 v[24:27], v[160:163], v[218:221], v[24:27]
	v_mfma_f32_16x16x32_bf16 v[12:15], v[152:155], v[226:229], v[12:15]
	v_mfma_f32_16x16x32_bf16 v[8:11], v[160:163], v[226:229], v[8:11]
	v_mfma_f32_16x16x32_bf16 v[52:55], v[164:167], v[198:201], v[52:55]
	v_mfma_f32_16x16x32_bf16 v[48:51], v[172:175], v[198:201], v[48:51]
	v_mfma_f32_16x16x32_bf16 v[36:39], v[164:167], v[206:209], v[36:39]
	v_mfma_f32_16x16x32_bf16 v[32:35], v[172:175], v[206:209], v[32:35]
	v_mfma_f32_16x16x32_bf16 v[20:23], v[164:167], v[214:217], v[20:23]
	v_mfma_f32_16x16x32_bf16 v[16:19], v[172:175], v[214:217], v[16:19]
	v_mfma_f32_16x16x32_bf16 v[4:7], v[164:167], v[222:225], v[4:7]
	v_mfma_f32_16x16x32_bf16 v[0:3], v[172:175], v[222:225], v[0:3]
	v_mfma_f32_16x16x32_bf16 v[52:55], v[168:171], v[202:205], v[52:55]
	v_mfma_f32_16x16x32_bf16 v[48:51], v[194:197], v[202:205], v[48:51]
	v_mfma_f32_16x16x32_bf16 v[36:39], v[168:171], v[210:213], v[36:39]
	v_mfma_f32_16x16x32_bf16 v[32:35], v[194:197], v[210:213], v[32:35]
	v_mfma_f32_16x16x32_bf16 v[20:23], v[168:171], v[218:221], v[20:23]
	v_mfma_f32_16x16x32_bf16 v[16:19], v[194:197], v[218:221], v[16:19]
	v_mfma_f32_16x16x32_bf16 v[4:7], v[168:171], v[226:229], v[4:7]
	v_mfma_f32_16x16x32_bf16 v[0:3], v[194:197], v[226:229], v[0:3]
	s_barrier
	s_add_i32 s53, s53, 2
	s_add_u32 s41, s41, 0x100
	s_addc_u32 s52, s52, 0
	s_add_u32 s46, s46, 0x100
	s_addc_u32 s47, s47, 0
	s_cmp_gt_u32 s53, 13
	s_cbranch_scc0 .LBB0_659
	s_and_b64 vcc, exec, s[16:17]
	s_cbranch_vccz .LBB0_662
	s_barrier

; #define PG8_STAGE(bufoff, gbase, voff) do { _Pragma("unroll") for (int _i = 0; _i < 2; ++_i) \
;         __builtin_amdgcn_global_load_lds((const unsigned*)((const char*)(gbase) + (voff)[_i]), (PG8_LAS unsigned*)(lds + (bufoff) + ldsw + _i * 8192), 16, 0, 0); } while (0)
; #define PG8_LDA(dst, b, h) do { _Pragma("unroll") for (int m = 0; m < 4; ++m) _Pragma("unroll") for (int k = 0; k < 2; ++k) dst[m][k] = *(const PG8_LAS bf16x8*)(lds + PG8_SA(b, h) + aoff + m * 2048 + k * 1024); } while (0)
; #define PG8_LDB(dst, b, h) do { _Pragma("unroll") for (int n = 0; n < 2; ++n) _Pragma("unroll") for (int k = 0; k < 2; ++k) dst[n][k] = *(const PG8_LAS bf16x8*)(lds + PG8_SB(b, h) + boff + n * 2048 + k * 1024); } while (0)
; #define PG8_MMA(ai, bj, At, Bt) do { __builtin_amdgcn_s_setprio(1); _Pragma("unroll") for (int m = 0; m < 4; ++m) _Pragma("unroll") for (int n = 0; n < 2; ++n) _Pragma("unroll") for (int k = 0; k < 2; ++k) \
;         acc[ai][bj][m][n] = __builtin_amdgcn_mfma_f32_16x16x32_bf16(Bt[n][k], At[m][k], acc[ai][bj][m][n], 0, 0, 0); __builtin_amdgcn_s_setprio(0); } while (0)
; #define PG8_WAIT_V(n) asm volatile("s_waitcnt vmcnt(" #n ")" ::: "memory")
; #define PG8_WAIT_L(n) asm volatile("s_waitcnt lgkmcnt(" #n ")" ::: "memory")
; template <class Epi, class Sched, bool ALIGN_EPI = false, bool SP2 = false>
; __device__ __forceinline__ void gemm_phase(PG8_LAS unsigned char* lds, const Gemm g, const Sched& S, const Epi& E) {
;     ...
;             const bool last = (t == nt - 2);
;             const char* a1 = cA + (size_t)(t + 1) * kstep;
;             const char* a2 = last ? nA : cA + (size_t)(t + 2) * kstep; const char* b2 = last ? nB : cB + (size_t)(t + 2) * kstep;
;             const char* a3 = a2 + kstep; const char* b3 = b2 + kstep;
;             if (last && has_next) S.a_ready(nxt);
;             if constexpr (SP2) {
;             PG8_LDB(B0, 0, 0); PG8_LDB(B1, 0, 1); PG8_SCHED; PG8_LDA(At, 0, 0); PG8_STAGE(PG8_SA(1, 1), a1 + hstep, voffA);
;             PG8_WAIT_V(8); PG8_WAIT_L(0); PG8_BAR; PG8_MMA(0, 0, At, B0); PG8_MMA(0, 1, At, B1); PG8_BAR; PG8_SCHED;
;             PG8_LDA(At, 0, 1); PG8_STAGE(PG8_SB(0, 0), b2, voffB); PG8_STAGE(PG8_SB(0, 1), b2 + hstep, voffB); PG8_STAGE(PG8_SA(0, 0), a2, voffA);
;             PG8_WAIT_V(8); PG8_WAIT_L(0); PG8_BAR; PG8_MMA(1, 0, At, B0); PG8_MMA(1, 1, At, B1); PG8_BAR; PG8_SCHED;
.LBB0_744:
	s_add_u32 s38, s4, 0xfff00080
	s_addc_u32 s39, s5, -1
	s_add_i32 s60, 0, 0x10000
	s_cmp_eq_u32 s59, 60
	s_cselect_b32 s57, s33, s39
	s_cselect_b32 s56, s34, s38
	s_cselect_b32 s39, s35, s58
	s_cselect_b32 s38, s49, s51
	s_add_i32 s62, 0, 0x14000
	v_add_u32_e32 v140, s60, v205
	v_add_u32_e32 v168, s62, v205
	ds_read_b128 v[120:123], v140
	ds_read_b128 v[132:135], v140 offset:1024
	ds_read_b128 v[136:139], v140 offset:2048
	ds_read_b128 v[140:143], v140 offset:3072
	ds_read_b128 v[144:147], v168
	ds_read_b128 v[148:151], v168 offset:1024
	ds_read_b128 v[152:155], v168 offset:2048
	ds_read_b128 v[168:171], v168 offset:3072
	v_lshl_add_u64 v[178:179], s[4:5], 0, v[166:167]
	s_add_i32 m0, s21, 0xc000
	ds_read_b128 v[172:175], v207
	ds_read_b128 v[194:197], v207 offset:1024
	ds_read_b128 v[198:201], v207 offset:2048
	ds_read_b128 v[208:211], v207 offset:3072
	ds_read_b128 v[212:215], v207 offset:4096
	ds_read_b128 v[216:219], v207 offset:5120
	ds_read_b128 v[220:223], v207 offset:6144
	ds_read_b128 v[224:227], v207 offset:7168
	global_load_lds_dwordx4 v[178:179], off
	v_lshl_add_u64 v[178:179], s[4:5], 0, v[164:165]
	s_add_i32 m0, s21, 0xe000
	s_nop 0
	global_load_lds_dwordx4 v[178:179], off
	s_waitcnt vmcnt(8)
	s_waitcnt lgkmcnt(0)
	s_barrier
	v_mfma_f32_16x16x32_bf16 v[128:131], v[120:123], v[172:175], v[128:131]
	v_mfma_f32_16x16x32_bf16 v[124:127], v[136:139], v[172:175], v[124:127]
	v_mfma_f32_16x16x32_bf16 v[108:111], v[120:123], v[198:201], v[108:111]
	v_mfma_f32_16x16x32_bf16 v[104:107], v[136:139], v[198:201], v[104:107]
	v_mfma_f32_16x16x32_bf16 v[92:95], v[120:123], v[212:215], v[92:95]
	v_mfma_f32_16x16x32_bf16 v[88:91], v[136:139], v[212:215], v[88:91]
	v_mfma_f32_16x16x32_bf16 v[76:79], v[120:123], v[220:223], v[76:79]
	v_mfma_f32_16x16x32_bf16 v[72:75], v[136:139], v[220:223], v[72:75]
	v_mfma_f32_16x16x32_bf16 v[128:131], v[132:135], v[194:197], v[128:131]
	v_mfma_f32_16x16x32_bf16 v[124:127], v[140:143], v[194:197], v[124:127]
	v_mfma_f32_16x16x32_bf16 v[108:111], v[132:135], v[208:211], v[108:111]
	v_mfma_f32_16x16x32_bf16 v[104:107], v[140:143], v[208:211], v[104:107]
	v_mfma_f32_16x16x32_bf16 v[92:95], v[132:135], v[216:219], v[92:95]
	v_mfma_f32_16x16x32_bf16 v[88:91], v[140:143], v[216:219], v[88:91]
	v_mfma_f32_16x16x32_bf16 v[76:79], v[132:135], v[224:227], v[76:79]
	v_mfma_f32_16x16x32_bf16 v[72:75], v[140:143], v[224:227], v[72:75]
	v_mfma_f32_16x16x32_bf16 v[116:119], v[144:147], v[172:175], v[116:119]
	v_mfma_f32_16x16x32_bf16 v[112:115], v[152:155], v[172:175], v[112:115]
	v_mfma_f32_16x16x32_bf16 v[100:103], v[144:147], v[198:201], v[100:103]
	v_mfma_f32_16x16x32_bf16 v[96:99], v[152:155], v[198:201], v[96:99]
	v_mfma_f32_16x16x32_bf16 v[84:87], v[144:147], v[212:215], v[84:87]
	v_mfma_f32_16x16x32_bf16 v[80:83], v[152:155], v[212:215], v[80:83]
	v_mfma_f32_16x16x32_bf16 v[68:71], v[144:147], v[220:223], v[68:71]
	v_mfma_f32_16x16x32_bf16 v[64:67], v[152:155], v[220:223], v[64:67]
	v_mfma_f32_16x16x32_bf16 v[116:119], v[148:151], v[194:197], v[116:119]
	v_mfma_f32_16x16x32_bf16 v[112:115], v[168:171], v[194:197], v[112:115]
	v_mfma_f32_16x16x32_bf16 v[100:103], v[148:151], v[208:211], v[100:103]
	v_mfma_f32_16x16x32_bf16 v[96:99], v[168:171], v[208:211], v[96:99]
	v_mfma_f32_16x16x32_bf16 v[84:87], v[148:151], v[216:219], v[84:87]
	v_mfma_f32_16x16x32_bf16 v[80:83], v[168:171], v[216:219], v[80:83]
	v_mfma_f32_16x16x32_bf16 v[68:71], v[148:151], v[224:227], v[68:71]
	v_mfma_f32_16x16x32_bf16 v[64:67], v[168:171], v[224:227], v[64:67]
	s_barrier
	s_add_i32 s60, s60, s20
	v_lshl_add_u64 v[178:179], s[38:39], 0, v[160:161]
	s_mov_b32 m0, s60
	ds_read_b128 v[172:175], v207 offset:16384
	ds_read_b128 v[194:197], v207 offset:17408
	ds_read_b128 v[198:201], v207 offset:18432
	ds_read_b128 v[208:211], v207 offset:19456
	ds_read_b128 v[212:215], v207 offset:20480
	ds_read_b128 v[216:219], v207 offset:21504
	ds_read_b128 v[220:223], v207 offset:22528
	ds_read_b128 v[224:227], v207 offset:23552
	global_load_lds_dwordx4 v[178:179], off
	s_add_i32 m0, s60, 0x2000
	s_add_u32 s60, s38, 0x100000
	v_lshl_add_u64 v[202:203], s[38:39], 0, v[156:157]
	s_addc_u32 s61, s39, 0
	s_add_i32 s62, s62, s20
	global_load_lds_dwordx4 v[202:203], off
	v_lshl_add_u64 v[228:229], s[60:61], 0, v[160:161]
	s_mov_b32 m0, s62
	v_lshl_add_u64 v[230:231], s[56:57], 0, v[158:159]
	global_load_lds_dwordx4 v[228:229], off
	v_lshl_add_u64 v[228:229], s[60:61], 0, v[156:157]
	s_add_i32 m0, s62, 0x2000
	s_nop 0
	global_load_lds_dwordx4 v[228:229], off
	v_lshl_add_u64 v[228:229], s[56:57], 0, v[162:163]
	s_mov_b32 m0, s21
	s_nop 0
	global_load_lds_dwordx4 v[228:229], off
	s_mov_b32 m0, s22
	s_nop 0
	global_load_lds_dwordx4 v[230:231], off
	s_waitcnt vmcnt(8)
	s_waitcnt lgkmcnt(0)
	s_barrier
; #define PG8_STAGE(bufoff, gbase, voff) do { _Pragma("unroll") for (int _i = 0; _i < 2; ++_i) \
;         __builtin_amdgcn_global_load_lds((const unsigned*)((const char*)(gbase) + (voff)[_i]), (PG8_LAS unsigned*)(lds + (bufoff) + ldsw + _i * 8192), 16, 0, 0); } while (0)
; #define PG8_LDA(dst, b, h) do { _Pragma("unroll") for (int m = 0; m < 4; ++m) _Pragma("unroll") for (int k = 0; k < 2; ++k) dst[m][k] = *(const PG8_LAS bf16x8*)(lds + PG8_SA(b, h) + aoff + m * 2048 + k * 1024); } while (0)
; #define PG8_LDB(dst, b, h) do { _Pragma("unroll") for (int n = 0; n < 2; ++n) _Pragma("unroll") for (int k = 0; k < 2; ++k) dst[n][k] = *(const PG8_LAS bf16x8*)(lds + PG8_SB(b, h) + boff + n * 2048 + k * 1024); } while (0)
; #define PG8_MMA(ai, bj, At, Bt) do { __builtin_amdgcn_s_setprio(1); _Pragma("unroll") for (int m = 0; m < 4; ++m) _Pragma("unroll") for (int n = 0; n < 2; ++n) _Pragma("unroll") for (int k = 0; k < 2; ++k) \
;         acc[ai][bj][m][n] = __builtin_amdgcn_mfma_f32_16x16x32_bf16(Bt[n][k], At[m][k], acc[ai][bj][m][n], 0, 0, 0); __builtin_amdgcn_s_setprio(0); } while (0)
; #define PG8_WAIT_V(n) asm volatile("s_waitcnt vmcnt(" #n ")" ::: "memory")
; #define PG8_WAIT_L(n) asm volatile("s_waitcnt lgkmcnt(" #n ")" ::: "memory")
; #define PG8_BAR __builtin_amdgcn_s_barrier()
; #define PG8_SCHED __builtin_amdgcn_sched_barrier(0)
; template <class Epi, class Sched, bool ALIGN_EPI = false, bool SP2 = false>
; __device__ __forceinline__ void gemm_phase(PG8_LAS unsigned char* lds, const Gemm g, const Sched& S, const Epi& E) {
;     ...
;             PG8_WAIT_V(8); PG8_WAIT_L(0); PG8_BAR; PG8_MMA(1, 0, At, B0); PG8_MMA(1, 1, At, B1); PG8_BAR; PG8_SCHED;
;             PG8_LDB(B0, 1, 0); PG8_LDB(B1, 1, 1); PG8_SCHED; PG8_LDA(At, 1, 0); PG8_STAGE(PG8_SA(0, 1), a2 + hstep, voffA);
;             PG8_WAIT_V(8); PG8_WAIT_L(0); PG8_BAR; PG8_MMA(0, 0, At, B0); PG8_MMA(0, 1, At, B1); PG8_BAR; PG8_SCHED;
	v_mfma_f32_16x16x32_bf16 v[60:63], v[120:123], v[172:175], v[60:63]
	v_mfma_f32_16x16x32_bf16 v[56:59], v[136:139], v[172:175], v[56:59]
	v_mfma_f32_16x16x32_bf16 v[44:47], v[120:123], v[198:201], v[44:47]
	v_mfma_f32_16x16x32_bf16 v[40:43], v[136:139], v[198:201], v[40:43]
	v_mfma_f32_16x16x32_bf16 v[28:31], v[120:123], v[212:215], v[28:31]
	v_mfma_f32_16x16x32_bf16 v[24:27], v[136:139], v[212:215], v[24:27]
	v_mfma_f32_16x16x32_bf16 v[12:15], v[120:123], v[220:223], v[12:15]
	v_mfma_f32_16x16x32_bf16 v[8:11], v[136:139], v[220:223], v[8:11]
	v_mfma_f32_16x16x32_bf16 v[60:63], v[132:135], v[194:197], v[60:63]
	v_mfma_f32_16x16x32_bf16 v[56:59], v[140:143], v[194:197], v[56:59]
	v_mfma_f32_16x16x32_bf16 v[44:47], v[132:135], v[208:211], v[44:47]
	v_mfma_f32_16x16x32_bf16 v[40:43], v[140:143], v[208:211], v[40:43]
	v_mfma_f32_16x16x32_bf16 v[28:31], v[132:135], v[216:219], v[28:31]
	v_mfma_f32_16x16x32_bf16 v[24:27], v[140:143], v[216:219], v[24:27]
	v_mfma_f32_16x16x32_bf16 v[12:15], v[132:135], v[224:227], v[12:15]
	v_mfma_f32_16x16x32_bf16 v[8:11], v[140:143], v[224:227], v[8:11]
	v_mfma_f32_16x16x32_bf16 v[52:55], v[144:147], v[172:175], v[52:55]
	v_mfma_f32_16x16x32_bf16 v[48:51], v[152:155], v[172:175], v[48:51]
	v_mfma_f32_16x16x32_bf16 v[36:39], v[144:147], v[198:201], v[36:39]
	v_mfma_f32_16x16x32_bf16 v[32:35], v[152:155], v[198:201], v[32:35]
	v_mfma_f32_16x16x32_bf16 v[20:23], v[144:147], v[212:215], v[20:23]
	v_mfma_f32_16x16x32_bf16 v[16:19], v[152:155], v[212:215], v[16:19]
	v_mfma_f32_16x16x32_bf16 v[4:7], v[144:147], v[220:223], v[4:7]
	v_mfma_f32_16x16x32_bf16 v[0:3], v[152:155], v[220:223], v[0:3]
	v_mfma_f32_16x16x32_bf16 v[52:55], v[148:151], v[194:197], v[52:55]
	v_mfma_f32_16x16x32_bf16 v[48:51], v[168:171], v[194:197], v[48:51]
	v_mfma_f32_16x16x32_bf16 v[36:39], v[148:151], v[208:211], v[36:39]
	v_mfma_f32_16x16x32_bf16 v[32:35], v[168:171], v[208:211], v[32:35]
	v_mfma_f32_16x16x32_bf16 v[20:23], v[148:151], v[216:219], v[20:23]
	v_mfma_f32_16x16x32_bf16 v[16:19], v[168:171], v[216:219], v[16:19]
	v_mfma_f32_16x16x32_bf16 v[4:7], v[148:151], v[224:227], v[4:7]
	v_mfma_f32_16x16x32_bf16 v[0:3], v[168:171], v[224:227], v[0:3]
	s_barrier
	s_add_i32 s60, 0, 0x18000
	s_add_i32 s61, 0, 0x1c000
	v_add_u32_e32 v140, s60, v205
	v_add_u32_e32 v168, s61, v205
	ds_read_b128 v[120:123], v140
	ds_read_b128 v[132:135], v140 offset:1024
	ds_read_b128 v[136:139], v140 offset:2048
	ds_read_b128 v[140:143], v140 offset:3072
	ds_read_b128 v[144:147], v168
	ds_read_b128 v[148:151], v168 offset:1024
	ds_read_b128 v[152:155], v168 offset:2048
	ds_read_b128 v[168:171], v168 offset:3072
	s_add_u32 s56, s56, 0x100000
	s_addc_u32 s57, s57, 0
	s_mov_b32 m0, s23
	v_lshl_add_u64 v[232:233], s[56:57], 0, v[162:163]
	ds_read_b128 v[172:175], v207 offset:32768
	ds_read_b128 v[194:197], v207 offset:33792
	ds_read_b128 v[198:201], v207 offset:34816
	ds_read_b128 v[208:211], v207 offset:35840
	ds_read_b128 v[212:215], v207 offset:36864
	ds_read_b128 v[216:219], v207 offset:37888
	ds_read_b128 v[220:223], v207 offset:38912
	ds_read_b128 v[224:227], v207 offset:39936
	global_load_lds_dwordx4 v[232:233], off
	v_lshl_add_u64 v[232:233], s[56:57], 0, v[158:159]
	s_mov_b32 m0, s24
	s_nop 0
	global_load_lds_dwordx4 v[232:233], off
	s_waitcnt vmcnt(8)
	s_waitcnt lgkmcnt(0)
	s_barrier
	v_mfma_f32_16x16x32_bf16 v[128:131], v[120:123], v[172:175], v[128:131]
	v_mfma_f32_16x16x32_bf16 v[124:127], v[136:139], v[172:175], v[124:127]
	v_mfma_f32_16x16x32_bf16 v[108:111], v[120:123], v[198:201], v[108:111]
	v_mfma_f32_16x16x32_bf16 v[104:107], v[136:139], v[198:201], v[104:107]
	v_mfma_f32_16x16x32_bf16 v[92:95], v[120:123], v[212:215], v[92:95]
	v_mfma_f32_16x16x32_bf16 v[88:91], v[136:139], v[212:215], v[88:91]
	v_mfma_f32_16x16x32_bf16 v[76:79], v[120:123], v[220:223], v[76:79]
	v_mfma_f32_16x16x32_bf16 v[72:75], v[136:139], v[220:223], v[72:75]
	v_mfma_f32_16x16x32_bf16 v[128:131], v[132:135], v[194:197], v[128:131]
	v_mfma_f32_16x16x32_bf16 v[124:127], v[140:143], v[194:197], v[124:127]
	v_mfma_f32_16x16x32_bf16 v[108:111], v[132:135], v[208:211], v[108:111]
	v_mfma_f32_16x16x32_bf16 v[104:107], v[140:143], v[208:211], v[104:107]
	v_mfma_f32_16x16x32_bf16 v[92:95], v[132:135], v[216:219], v[92:95]
	v_mfma_f32_16x16x32_bf16 v[88:91], v[140:143], v[216:219], v[88:91]
	v_mfma_f32_16x16x32_bf16 v[76:79], v[132:135], v[224:227], v[76:79]
	v_mfma_f32_16x16x32_bf16 v[72:75], v[140:143], v[224:227], v[72:75]
	v_mfma_f32_16x16x32_bf16 v[116:119], v[144:147], v[172:175], v[116:119]
	v_mfma_f32_16x16x32_bf16 v[112:115], v[152:155], v[172:175], v[112:115]
	v_mfma_f32_16x16x32_bf16 v[100:103], v[144:147], v[198:201], v[100:103]
	v_mfma_f32_16x16x32_bf16 v[96:99], v[152:155], v[198:201], v[96:99]
	v_mfma_f32_16x16x32_bf16 v[84:87], v[144:147], v[212:215], v[84:87]
	v_mfma_f32_16x16x32_bf16 v[80:83], v[152:155], v[212:215], v[80:83]
	v_mfma_f32_16x16x32_bf16 v[68:71], v[144:147], v[220:223], v[68:71]
	v_mfma_f32_16x16x32_bf16 v[64:67], v[152:155], v[220:223], v[64:67]
	v_mfma_f32_16x16x32_bf16 v[116:119], v[148:151], v[194:197], v[116:119]
	v_mfma_f32_16x16x32_bf16 v[112:115], v[168:171], v[194:197], v[112:115]
	v_mfma_f32_16x16x32_bf16 v[100:103], v[148:151], v[208:211], v[100:103]
	v_mfma_f32_16x16x32_bf16 v[96:99], v[168:171], v[208:211], v[96:99]
	v_mfma_f32_16x16x32_bf16 v[84:87], v[148:151], v[216:219], v[84:87]
	v_mfma_f32_16x16x32_bf16 v[80:83], v[168:171], v[216:219], v[80:83]
	v_mfma_f32_16x16x32_bf16 v[68:71], v[148:151], v[224:227], v[68:71]
	v_mfma_f32_16x16x32_bf16 v[64:67], v[168:171], v[224:227], v[64:67]
	s_barrier
; #define PG8_STAGE(bufoff, gbase, voff) do { _Pragma("unroll") for (int _i = 0; _i < 2; ++_i) \
;         __builtin_amdgcn_global_load_lds((const unsigned*)((const char*)(gbase) + (voff)[_i]), (PG8_LAS unsigned*)(lds + (bufoff) + ldsw + _i * 8192), 16, 0, 0); } while (0)
; #define PG8_LDA(dst, b, h) do { _Pragma("unroll") for (int m = 0; m < 4; ++m) _Pragma("unroll") for (int k = 0; k < 2; ++k) dst[m][k] = *(const PG8_LAS bf16x8*)(lds + PG8_SA(b, h) + aoff + m * 2048 + k * 1024); } while (0)
; #define PG8_MMA(ai, bj, At, Bt) do { __builtin_amdgcn_s_setprio(1); _Pragma("unroll") for (int m = 0; m < 4; ++m) _Pragma("unroll") for (int n = 0; n < 2; ++n) _Pragma("unroll") for (int k = 0; k < 2; ++k) \
;         acc[ai][bj][m][n] = __builtin_amdgcn_mfma_f32_16x16x32_bf16(Bt[n][k], At[m][k], acc[ai][bj][m][n], 0, 0, 0); __builtin_amdgcn_s_setprio(0); } while (0)
; #define PG8_WAIT_V(n) asm volatile("s_waitcnt vmcnt(" #n ")" ::: "memory")
; #define PG8_WAIT_L(n) asm volatile("s_waitcnt lgkmcnt(" #n ")" ::: "memory")
; #define PG8_BAR __builtin_amdgcn_s_barrier()
; #define PG8_SCHED __builtin_amdgcn_sched_barrier(0)
; template <class Epi, class Sched, bool ALIGN_EPI = false, bool SP2 = false>
; __device__ __forceinline__ void gemm_phase(PG8_LAS unsigned char* lds, const Gemm g, const Sched& S, const Epi& E) {
;     ...
;             PG8_LDA(At, 1, 1); PG8_STAGE(PG8_SB(1, 0), b3, voffB); PG8_STAGE(PG8_SB(1, 1), b3 + hstep, voffB); PG8_STAGE(PG8_SA(1, 0), a3, voffA);
;             PG8_WAIT_V(8); PG8_WAIT_L(0); PG8_BAR; PG8_MMA(1, 0, At, B0); PG8_MMA(1, 1, At, B1); PG8_BAR; PG8_SCHED;
;     ...
;         if constexpr (ALIGN_EPI) { if (wr == 0) PG8_BAR; }
	s_add_i32 s56, s60, s20
	v_lshl_add_u64 v[178:179], v[178:179], 0, s[36:37]
	s_mov_b32 m0, s56
	ds_read_b128 v[172:175], v207 offset:49152
	ds_read_b128 v[194:197], v207 offset:50176
	ds_read_b128 v[198:201], v207 offset:51200
	ds_read_b128 v[208:211], v207 offset:52224
	ds_read_b128 v[212:215], v207 offset:53248
	ds_read_b128 v[216:219], v207 offset:54272
	ds_read_b128 v[220:223], v207 offset:55296
	ds_read_b128 v[224:227], v207 offset:56320
	global_load_lds_dwordx4 v[178:179], off
	s_add_i32 m0, s56, 0x2000
	s_add_u32 s38, s38, 0x100080
	v_lshl_add_u64 v[178:179], v[202:203], 0, s[36:37]
	s_addc_u32 s39, s39, 0
	s_add_i32 s56, s61, s20
	global_load_lds_dwordx4 v[178:179], off
	v_lshl_add_u64 v[178:179], s[38:39], 0, v[160:161]
	s_mov_b32 m0, s56
	s_nop 0
	global_load_lds_dwordx4 v[178:179], off
	v_lshl_add_u64 v[178:179], s[38:39], 0, v[156:157]
	s_add_i32 m0, s56, 0x2000
	s_nop 0
	global_load_lds_dwordx4 v[178:179], off
	v_lshl_add_u64 v[178:179], v[228:229], 0, s[36:37]
	s_mov_b32 m0, s29
	s_nop 0
	global_load_lds_dwordx4 v[178:179], off
	v_lshl_add_u64 v[178:179], v[230:231], 0, s[36:37]
	s_mov_b32 m0, s30
	s_nop 0
	global_load_lds_dwordx4 v[178:179], off
	s_waitcnt vmcnt(8)
	s_waitcnt lgkmcnt(0)
	s_barrier
	v_mfma_f32_16x16x32_bf16 v[60:63], v[120:123], v[172:175], v[60:63]
	v_mfma_f32_16x16x32_bf16 v[56:59], v[136:139], v[172:175], v[56:59]
	v_mfma_f32_16x16x32_bf16 v[44:47], v[120:123], v[198:201], v[44:47]
	v_mfma_f32_16x16x32_bf16 v[40:43], v[136:139], v[198:201], v[40:43]
	v_mfma_f32_16x16x32_bf16 v[28:31], v[120:123], v[212:215], v[28:31]
	v_mfma_f32_16x16x32_bf16 v[24:27], v[136:139], v[212:215], v[24:27]
	v_mfma_f32_16x16x32_bf16 v[12:15], v[120:123], v[220:223], v[12:15]
	v_mfma_f32_16x16x32_bf16 v[8:11], v[136:139], v[220:223], v[8:11]
	v_mfma_f32_16x16x32_bf16 v[60:63], v[132:135], v[194:197], v[60:63]
	v_mfma_f32_16x16x32_bf16 v[56:59], v[140:143], v[194:197], v[56:59]
	v_mfma_f32_16x16x32_bf16 v[44:47], v[132:135], v[208:211], v[44:47]
	v_mfma_f32_16x16x32_bf16 v[40:43], v[140:143], v[208:211], v[40:43]
	v_mfma_f32_16x16x32_bf16 v[28:31], v[132:135], v[216:219], v[28:31]
	v_mfma_f32_16x16x32_bf16 v[24:27], v[140:143], v[216:219], v[24:27]
	v_mfma_f32_16x16x32_bf16 v[12:15], v[132:135], v[224:227], v[12:15]
	v_mfma_f32_16x16x32_bf16 v[8:11], v[140:143], v[224:227], v[8:11]
	v_mfma_f32_16x16x32_bf16 v[52:55], v[144:147], v[172:175], v[52:55]
	v_mfma_f32_16x16x32_bf16 v[48:51], v[152:155], v[172:175], v[48:51]
	v_mfma_f32_16x16x32_bf16 v[36:39], v[144:147], v[198:201], v[36:39]
	v_mfma_f32_16x16x32_bf16 v[32:35], v[152:155], v[198:201], v[32:35]
	v_mfma_f32_16x16x32_bf16 v[20:23], v[144:147], v[212:215], v[20:23]
	v_mfma_f32_16x16x32_bf16 v[16:19], v[152:155], v[212:215], v[16:19]
	v_mfma_f32_16x16x32_bf16 v[4:7], v[144:147], v[220:223], v[4:7]
	v_mfma_f32_16x16x32_bf16 v[0:3], v[152:155], v[220:223], v[0:3]
	v_mfma_f32_16x16x32_bf16 v[52:55], v[148:151], v[194:197], v[52:55]
	v_mfma_f32_16x16x32_bf16 v[48:51], v[168:171], v[194:197], v[48:51]
	v_mfma_f32_16x16x32_bf16 v[36:39], v[148:151], v[208:211], v[36:39]
	v_mfma_f32_16x16x32_bf16 v[32:35], v[168:171], v[208:211], v[32:35]
	v_mfma_f32_16x16x32_bf16 v[20:23], v[148:151], v[216:219], v[20:23]
	v_mfma_f32_16x16x32_bf16 v[16:19], v[168:171], v[216:219], v[16:19]
	v_mfma_f32_16x16x32_bf16 v[4:7], v[148:151], v[224:227], v[4:7]
	v_mfma_f32_16x16x32_bf16 v[0:3], v[168:171], v[224:227], v[0:3]
	s_barrier
	s_add_i32 s59, s59, 2
	s_add_u32 s51, s51, 0x100
	s_addc_u32 s58, s58, 0
	s_add_u32 s4, s4, 0x100
	s_addc_u32 s5, s5, 0
	s_cmp_gt_u32 s59, 61
	s_cbranch_scc0 .LBB0_744
	s_and_b64 vcc, exec, s[42:43]
	s_cbranch_vccz .LBB0_747
	s_barrier
